# attention step loop unrolled by ring slot (4 copies per role): K/V fragment reads use ds offset immediates, per-step address VALU and read-slot rotation removed
# speedup vs baseline: 1.0062x; 1.0062x over previous
; #define RING_ISSUE(SI) do { int kbi = kb0 + (SI) * 32; if (kbi > kb_last) kbi = kb_last; const int slot = (SI) % 3; \
;           const h16* srcp = wave < 4 ? kbase + (size_t)kbi * LDH + k_src_off : vT + (size_t)(kbi >> 5) * 2048 + v_src_off; \
;           __builtin_amdgcn_global_load_lds((const unsigned*)srcp, (LAS unsigned*)(ring + slot * 8192 + stage_dst), 16, 0, 0); } while (0)
; DI void attn_phase(const Params& p, const int layer, const int wid_s) {
;     ...
;       unsigned kread[2][2], vread[4];
; #pragma unroll
;       for (int kt = 0; kt < 2; ++kt)
; #pragma unroll
;         for (int ks = 0; ks < 2; ++ks) { const int r = kt * 16 + fr, c = ks * 4 + fq; kread[kt][ks] = (unsigned)(r * 128 + ((c ^ (r & 7)) * 16)); }
; #pragma unroll
;       for (int dt = 0; dt < 4; ++dt) { const int r = dt * 16 + fr; vread[dt] = (unsigned)(4096 + r * 64 + ((fq ^ ((r >> 2) & 3)) * 16)); }
;     ...
; #pragma unroll 1
;         for (int si = 0; si < nsteps; ++si) {
;           asm volatile("s_waitcnt vmcnt(1) lgkmcnt(0)" ::: "memory");
;           __builtin_amdgcn_s_barrier();
;           asm volatile("" ::: "memory");
;           RING_ISSUE(si + 2);
.LBB0_349:
	v_add_u32_e32 v0, 0x19880, v185
	v_add_u32_e32 v64, 0x19880, v184
	v_add_u32_e32 v65, 0x19880, v183
	s_and_b64 vcc, exec, s[30:31]
	s_cbranch_vccz .Lat_ytop
	s_branch .Lat_xtop

; #define LAS __attribute__((address_space(3)))
; template <bool SEL, bool GEN>
; DI void attn_step(const KF& kv, const int kb, const int t, const int lane, const bool selbit,
;                   const LAS float* tabh, const half8 (&q)[2][2], f32x4 (&O)[2][4], const float (&nR)[2], float (&l)[2]) {
;     ...
;   for (int hp = 0; hp < 2; ++hp) {
;     float nm = nR[hp];
;     if (SEL) nm = selbit ? nm : MASKV;
;     const f32x4 c0 = {nm, nm, nm, nm};
; DI void attn_phase(const Params& p, const int layer, const int wid_s) {
;     ...
;           LAS unsigned char* slotp = ring + (si % 3) * 8192;
;           KF kv;
; #pragma unroll
;           for (int kt = 0; kt < 2; ++kt)
; #pragma unroll
;             for (int ks = 0; ks < 2; ++ks) kv.k[kt][ks] = *(const LAS half8*)(slotp + kread[kt][ks]);
; #pragma unroll
;           for (int dt = 0; dt < 4; ++dt) kv.v[dt] = *(const LAS half8*)(slotp + vread[dt]);
;           if (br == 1) {
;             const bool bit = (selmask >> (kb >> 6)) & 1u;
.Lat_nogi_xt0:
	s_bitcmp1_b32 s12, 0
	s_cbranch_scc0 .Lat_xskip0
	ds_read_b128 v[96:99], v0 offset:0
	ds_read_b128 v[92:95], v64 offset:0
	ds_read_b128 v[88:91], v0 offset:2048
	ds_read_b128 v[84:87], v64 offset:2048
	s_lshr_b32 s10, s45, 6
	s_cmp_eq_u32 s10, s13
	s_cbranch_scc1 .Lat_cok_x0
	s_mov_b32 s13, s10
	v_bfe_u32 v66, v244, s10, 1
	v_cmp_ne_u32_e32 vcc, 0, v66
	s_nop 1
	v_cndmask_b32_e32 v128, v4, v242, vcc
	v_cndmask_b32_e32 v132, v4, v243, vcc
	v_cndmask_b32_e32 v129, v4, v242, vcc
	v_cndmask_b32_e32 v133, v4, v243, vcc
	v_cndmask_b32_e32 v130, v4, v242, vcc
	v_cndmask_b32_e32 v134, v4, v243, vcc
	v_cndmask_b32_e32 v131, v4, v242, vcc
	v_cndmask_b32_e32 v135, v4, v243, vcc

; #define MFMA16(a, b, c) __builtin_amdgcn_mfma_f32_16x16x32_f16((a), (b), (c), 0, 0, 0)
; #define RING_ISSUE(SI) do { int kbi = kb0 + (SI) * 32; if (kbi > kb_last) kbi = kb_last; const int slot = (SI) % 3; \
;           const h16* srcp = wave < 4 ? kbase + (size_t)kbi * LDH + k_src_off : vT + (size_t)(kbi >> 5) * 2048 + v_src_off; \
;           __builtin_amdgcn_global_load_lds((const unsigned*)srcp, (LAS unsigned*)(ring + slot * 8192 + stage_dst), 16, 0, 0); } while (0)
; template <bool SEL, bool GEN>
; DI void attn_step(const KF& kv, const int kb, const int t, const int lane, const bool selbit,
;                   const LAS float* tabh, const half8 (&q)[2][2], f32x4 (&O)[2][4], const float (&nR)[2], float (&l)[2]) {
;     ...
;       s[hp][kt] = MFMA16(kv.k[kt][0], q[hp][0], c0);
;       s[hp][kt] = MFMA16(kv.k[kt][1], q[hp][1], s[hp][kt]);
;     }
;   }
;   if (GEN) {
;     const int d0 = t - kb - fq * 4;
; #pragma unroll
;     for (int kt = 0; kt < 2; ++kt)
; #pragma unroll
;       for (int j = 0; j < 4; ++j) {
;         const int dist = d0 - (kt * 16 + j);
;         const bool bad = SEL ? (dist < 0) : ((unsigned)dist >= 512u);
;         const int ix = bad ? 130 : (dist > 128 ? 128 : dist);
; #pragma unroll
;         for (int hp = 0; hp < 2; ++hp) s[hp][kt][j] += tabh[hp * 132 + ix];
;       }
;   }
;   half8 pf[2];
; #pragma unroll
;   for (int hp = 0; hp < 2; ++hp) {
;     f32x4 p0, p1;
; #pragma unroll
;     for (int j = 0; j < 4; ++j) { p0[j] = __builtin_amdgcn_exp2f(s[hp][0][j]); p1[j] = __builtin_amdgcn_exp2f(s[hp][1][j]); }
;     l[hp] += ((p0[0] + p0[1]) + (p0[2] + p0[3])) + ((p1[0] + p1[1]) + (p1[2] + p1[3]));
;     pf[hp] = pack8(p0, p1);
;   }
; #pragma unroll
;   for (int dt = 0; dt < 4; ++dt)
; #pragma unroll
;     for (int hp = 0; hp < 2; ++hp) O[hp][dt] = MFMA16(kv.v[dt], pf[hp], O[hp][dt]);
; DI void attn_phase(const Params& p, const int layer, const int wid_s) {
;     ...
;         for (int si = 0; si < nsteps; ++si) {
;           asm volatile("s_waitcnt vmcnt(1) lgkmcnt(0)" ::: "memory");
;           __builtin_amdgcn_s_barrier();
;           asm volatile("" ::: "memory");
;           RING_ISSUE(si + 2);
;           const int kb = kb0 + si * 32;
;           if (kb > kmax_w || kb < lo_w) continue;
;           if (br == 1 && kb + 31 + 128 <= t0 && __ballot((selmask >> (kb >> 6)) & 1u) == 0ull) continue;
.Lat_noga_xa0:
	v_exp_f32_e32 v198, v100
	v_exp_f32_e32 v199, v101
	v_exp_f32_e32 v200, v102
	v_exp_f32_e32 v201, v103
	v_exp_f32_e32 v202, v104
	v_exp_f32_e32 v203, v105
	v_exp_f32_e32 v204, v106
	v_exp_f32_e32 v205, v107
	v_exp_f32_e32 v206, v108
	v_exp_f32_e32 v207, v109
	v_exp_f32_e32 v208, v110
	v_exp_f32_e32 v209, v111
	v_exp_f32_e32 v210, v112
	v_exp_f32_e32 v211, v113
	v_exp_f32_e32 v212, v114
	v_exp_f32_e32 v213, v115
	v_cvt_pkrtz_f16_f32 v120, v198, v199
	v_cvt_pkrtz_f16_f32 v121, v200, v201
	v_cvt_pkrtz_f16_f32 v122, v202, v203
	v_cvt_pkrtz_f16_f32 v123, v204, v205
	v_cvt_pkrtz_f16_f32 v124, v206, v207
	v_cvt_pkrtz_f16_f32 v125, v208, v209
	v_cvt_pkrtz_f16_f32 v126, v210, v211
	v_cvt_pkrtz_f16_f32 v127, v212, v213
	s_waitcnt lgkmcnt(0)
	s_and_b32 s44, s12, 2
	s_or_b32 s44, s44, 1
	v_mfma_f32_16x16x32_f16 v[100:103], v[96:99], v[8:11], v[128:131]
	s_add_i32 s8, s45, 64
	s_min_i32 s8, s8, s14
	s_mul_i32 s8, s8, s42
	s_mov_b32 s9, 0
	v_mfma_f32_16x16x32_f16 v[104:107], v[88:91], v[8:11], v[128:131]
	v_lshl_add_u64 v[238:239], v[240:241], 0, s[8:9]
	s_add_i32 m0, s43, s22
	s_nop 0
	global_load_lds_dwordx4 v[238:239], off
	v_mfma_f32_16x16x32_f16 v[108:111], v[96:99], v[16:19], v[132:135]
	s_add_i32 s43, s43, 0x2000
	s_cmp_eq_u32 s43, 0x1f880
	s_cselect_b32 s43, 0x20080, s43
	s_cmp_eq_u32 s43, 0x22080
	s_cselect_b32 s43, 0x19880, s43
	v_mfma_f32_16x16x32_f16 v[112:115], v[88:91], v[16:19], v[132:135]
	s_add_i32 s45, s45, 32
	s_add_i32 s41, s41, -1
	s_add_i32 s10, s45, 0x9f
	s_cmp_gt_i32 s10, s51
	v_mfma_f32_16x16x32_f16 v[100:103], v[92:95], v[12:15], v[100:103]
	s_cselect_b32 s11, 2, 0
	s_add_i32 s10, s45, 0x1f1
	s_cmp_le_i32 s10, s51
	s_cselect_b32 s10, 2, 0
	v_mfma_f32_16x16x32_f16 v[104:107], v[84:87], v[12:15], v[104:107]
	s_and_b32 s10, s10, s4
	s_or_b32 s11, s11, s10
	s_lshr_b32 s10, s45, 6
	v_bfe_u32 v66, v244, s10, 1
	v_cmp_ne_u32_e32 vcc, 0, v66
	v_mfma_f32_16x16x32_f16 v[108:111], v[92:95], v[20:23], v[108:111]
	s_cmp_lg_u64 vcc, 0
	s_cselect_b32 s10, 1, 0
	s_lshr_b32 s9, s11, 1
	s_or_b32 s10, s10, s9
	v_mfma_f32_16x16x32_f16 v[112:115], v[84:87], v[20:23], v[112:115]
	s_cmp_le_i32 s45, s15
	s_cselect_b32 s10, s10, 0
	s_cmp_ge_i32 s45, s40
	s_cselect_b32 s10, s10, 0
	s_or_b32 s12, s11, s10
	v_mfma_f32_16x16x32_f16 v[60:63], v[80:83], v[120:123], v[60:63]
	v_add_f32_e32 v214, v214, v198
	v_add_f32_e32 v215, v215, v199
	v_mfma_f32_16x16x32_f16 v[56:59], v[76:79], v[120:123], v[56:59]
	v_add_f32_e32 v216, v216, v200
	v_add_f32_e32 v217, v217, v201
	v_mfma_f32_16x16x32_f16 v[52:55], v[72:75], v[120:123], v[52:55]
	v_add_f32_e32 v214, v214, v202
	v_add_f32_e32 v215, v215, v203
	v_mfma_f32_16x16x32_f16 v[48:51], v[68:71], v[120:123], v[48:51]
	v_add_f32_e32 v216, v216, v204
	v_add_f32_e32 v217, v217, v205
	v_mfma_f32_16x16x32_f16 v[44:47], v[80:83], v[124:127], v[44:47]
	v_add_f32_e32 v218, v218, v206
	v_add_f32_e32 v219, v219, v207
	v_mfma_f32_16x16x32_f16 v[40:43], v[76:79], v[124:127], v[40:43]
	v_add_f32_e32 v220, v220, v208
	v_add_f32_e32 v221, v221, v209
	v_mfma_f32_16x16x32_f16 v[36:39], v[72:75], v[124:127], v[36:39]
	v_add_f32_e32 v218, v218, v210
	v_add_f32_e32 v219, v219, v211
	v_mfma_f32_16x16x32_f16 v[32:35], v[68:71], v[124:127], v[32:35]
	v_add_f32_e32 v220, v220, v212
	v_add_f32_e32 v221, v221, v213
	ds_read_b128 v[80:83], v65 offset:4096
	ds_read_b128 v[76:79], v65 offset:5120
	ds_read_b128 v[72:75], v65 offset:6144
	ds_read_b128 v[68:71], v65 offset:7168
	s_cmp_lg_u32 s41, 0
	s_cbranch_scc1 .Lat_xtop1
	s_branch .Lat_xexit
.Lat_xb0:
	s_waitcnt lgkmcnt(0)
	s_and_b32 s44, s12, 2
	s_or_b32 s44, s44, 1
	v_mfma_f32_16x16x32_f16 v[100:103], v[96:99], v[8:11], v[128:131]
	s_add_i32 s8, s45, 64
	s_min_i32 s8, s8, s14
	s_mul_i32 s8, s8, s42
	s_mov_b32 s9, 0
	v_mfma_f32_16x16x32_f16 v[104:107], v[88:91], v[8:11], v[128:131]
	v_lshl_add_u64 v[238:239], v[240:241], 0, s[8:9]
	s_add_i32 m0, s43, s22
	s_nop 0
	global_load_lds_dwordx4 v[238:239], off
	v_mfma_f32_16x16x32_f16 v[108:111], v[96:99], v[16:19], v[132:135]
	s_add_i32 s43, s43, 0x2000
	s_cmp_eq_u32 s43, 0x1f880
	s_cselect_b32 s43, 0x20080, s43
	s_cmp_eq_u32 s43, 0x22080
	s_cselect_b32 s43, 0x19880, s43
	v_mfma_f32_16x16x32_f16 v[112:115], v[88:91], v[16:19], v[132:135]
	s_add_i32 s45, s45, 32
	s_add_i32 s41, s41, -1
	s_add_i32 s10, s45, 0x9f
	s_cmp_gt_i32 s10, s51
	v_mfma_f32_16x16x32_f16 v[100:103], v[92:95], v[12:15], v[100:103]
	s_cselect_b32 s11, 2, 0
	s_add_i32 s10, s45, 0x1f1
	s_cmp_le_i32 s10, s51
	s_cselect_b32 s10, 2, 0
	v_mfma_f32_16x16x32_f16 v[104:107], v[84:87], v[12:15], v[104:107]
	s_and_b32 s10, s10, s4
	s_or_b32 s11, s11, s10
	s_lshr_b32 s10, s45, 6
	v_bfe_u32 v66, v244, s10, 1
	v_cmp_ne_u32_e32 vcc, 0, v66
	v_mfma_f32_16x16x32_f16 v[108:111], v[92:95], v[20:23], v[108:111]
	s_cmp_lg_u64 vcc, 0
	s_cselect_b32 s10, 1, 0
	s_lshr_b32 s9, s11, 1
	s_or_b32 s10, s10, s9
	v_mfma_f32_16x16x32_f16 v[112:115], v[84:87], v[20:23], v[112:115]
	s_cmp_le_i32 s45, s15
	s_cselect_b32 s10, s10, 0
	s_cmp_ge_i32 s45, s40
	s_cselect_b32 s10, s10, 0
	s_or_b32 s12, s11, s10
	ds_read_b128 v[80:83], v65 offset:4096
	ds_read_b128 v[76:79], v65 offset:5120
	ds_read_b128 v[72:75], v65 offset:6144
	ds_read_b128 v[68:71], v65 offset:7168
	s_cmp_lg_u32 s41, 0
	s_cbranch_scc1 .Lat_xtop1
	s_branch .Lat_xexit

; #define MFMA16(a, b, c) __builtin_amdgcn_mfma_f32_16x16x32_f16((a), (b), (c), 0, 0, 0)
; template <bool SEL, bool GEN>
; DI void attn_step(const KF& kv, const int kb, const int t, const int lane, const bool selbit,
;                   const LAS float* tabh, const half8 (&q)[2][2], f32x4 (&O)[2][4], const float (&nR)[2], float (&l)[2]) {
;     ...
; #pragma unroll
;   for (int dt = 0; dt < 4; ++dt)
; #pragma unroll
;     for (int hp = 0; hp < 2; ++hp) O[hp][dt] = MFMA16(kv.v[dt], pf[hp], O[hp][dt]);
; DI void attn_phase(const Params& p, const int layer, const int wid_s) {
;     ...
;           if (kb > kmax_w || kb < lo_w) continue;
;           if (br == 1 && kb + 31 + 128 <= t0 && __ballot((selmask >> (kb >> 6)) & 1u) == 0ull) continue;
.Lat_noga_xc0:
	v_exp_f32_e32 v198, v100
	v_exp_f32_e32 v199, v101
	v_exp_f32_e32 v200, v102
	v_exp_f32_e32 v201, v103
	v_exp_f32_e32 v202, v104
	v_exp_f32_e32 v203, v105
	v_exp_f32_e32 v204, v106
	v_exp_f32_e32 v205, v107
	v_exp_f32_e32 v206, v108
	v_exp_f32_e32 v207, v109
	v_exp_f32_e32 v208, v110
	v_exp_f32_e32 v209, v111
	v_exp_f32_e32 v210, v112
	v_exp_f32_e32 v211, v113
	v_exp_f32_e32 v212, v114
	v_exp_f32_e32 v213, v115
	v_cvt_pkrtz_f16_f32 v120, v198, v199
	v_cvt_pkrtz_f16_f32 v121, v200, v201
	v_cvt_pkrtz_f16_f32 v122, v202, v203
	v_cvt_pkrtz_f16_f32 v123, v204, v205
	v_cvt_pkrtz_f16_f32 v124, v206, v207
	v_cvt_pkrtz_f16_f32 v125, v208, v209
	v_cvt_pkrtz_f16_f32 v126, v210, v211
	v_cvt_pkrtz_f16_f32 v127, v212, v213
	s_waitcnt lgkmcnt(0)
	v_mfma_f32_16x16x32_f16 v[60:63], v[80:83], v[120:123], v[60:63]
	v_add_f32_e32 v214, v214, v198
	v_add_f32_e32 v215, v215, v199
	v_add_f32_e32 v216, v216, v200
	v_add_f32_e32 v217, v217, v201
	v_add_f32_e32 v214, v214, v202
	v_add_f32_e32 v215, v215, v203
	v_mfma_f32_16x16x32_f16 v[56:59], v[76:79], v[120:123], v[56:59]
	v_add_f32_e32 v216, v216, v204
	v_add_f32_e32 v217, v217, v205
	v_add_f32_e32 v218, v218, v206
	v_add_f32_e32 v219, v219, v207
	v_add_f32_e32 v220, v220, v208
	v_add_f32_e32 v221, v221, v209
	v_mfma_f32_16x16x32_f16 v[52:55], v[72:75], v[120:123], v[52:55]
	v_add_f32_e32 v218, v218, v210
	v_add_f32_e32 v219, v219, v211
	v_add_f32_e32 v220, v220, v212
	v_add_f32_e32 v221, v221, v213
	s_add_i32 s8, s45, 64
	s_min_i32 s8, s8, s14
	s_mul_i32 s8, s8, s42
	v_mfma_f32_16x16x32_f16 v[48:51], v[68:71], v[120:123], v[48:51]
	s_mov_b32 s9, 0
	v_lshl_add_u64 v[238:239], v[240:241], 0, s[8:9]
	s_add_i32 m0, s43, s22
	s_nop 0
	global_load_lds_dwordx4 v[238:239], off
	s_add_i32 s43, s43, 0x2000
	v_mfma_f32_16x16x32_f16 v[44:47], v[80:83], v[124:127], v[44:47]
	s_cmp_eq_u32 s43, 0x1f880
	s_cselect_b32 s43, 0x20080, s43
	s_cmp_eq_u32 s43, 0x22080
	s_cselect_b32 s43, 0x19880, s43
	s_add_i32 s45, s45, 32
	s_add_i32 s41, s41, -1
	v_mfma_f32_16x16x32_f16 v[40:43], v[76:79], v[124:127], v[40:43]
	s_add_i32 s10, s45, 0x9f
	s_cmp_gt_i32 s10, s51
	s_cselect_b32 s11, 2, 0
	s_add_i32 s10, s45, 0x1f1
	s_cmp_le_i32 s10, s51
	s_cselect_b32 s10, 2, 0
	s_and_b32 s10, s10, s4
	v_mfma_f32_16x16x32_f16 v[36:39], v[72:75], v[124:127], v[36:39]
	s_or_b32 s11, s11, s10
	s_lshr_b32 s10, s45, 6
	v_bfe_u32 v66, v244, s10, 1
	v_cmp_ne_u32_e32 vcc, 0, v66
	s_cmp_lg_u64 vcc, 0
	s_cselect_b32 s10, 1, 0
	v_mfma_f32_16x16x32_f16 v[32:35], v[68:71], v[124:127], v[32:35]
	s_lshr_b32 s9, s11, 1
	s_or_b32 s10, s10, s9
	s_cmp_le_i32 s45, s15
	s_cselect_b32 s10, s10, 0
	s_cmp_ge_i32 s45, s40
	s_cselect_b32 s10, s10, 0
	s_or_b32 s12, s11, s10
	s_mov_b32 s44, 0
	s_cmp_lg_u32 s41, 0
	s_cbranch_scc1 .Lat_xtop1
	s_branch .Lat_xexit
.Lat_xd0:
	s_add_i32 s8, s45, 64
	s_min_i32 s8, s8, s14
	s_mul_i32 s8, s8, s42
	s_mov_b32 s9, 0
	v_lshl_add_u64 v[238:239], v[240:241], 0, s[8:9]
	s_add_i32 m0, s43, s22
	s_nop 0
	global_load_lds_dwordx4 v[238:239], off
	s_add_i32 s43, s43, 0x2000
	s_cmp_eq_u32 s43, 0x1f880
	s_cselect_b32 s43, 0x20080, s43
	s_cmp_eq_u32 s43, 0x22080
	s_cselect_b32 s43, 0x19880, s43
	s_add_i32 s45, s45, 32
	s_add_i32 s41, s41, -1
	s_add_i32 s10, s45, 0x9f
	s_cmp_gt_i32 s10, s51
	s_cselect_b32 s11, 2, 0
	s_add_i32 s10, s45, 0x1f1
	s_cmp_le_i32 s10, s51
	s_cselect_b32 s10, 2, 0
	s_and_b32 s10, s10, s4
	s_or_b32 s11, s11, s10
	s_lshr_b32 s10, s45, 6
	v_bfe_u32 v66, v244, s10, 1
	v_cmp_ne_u32_e32 vcc, 0, v66
	s_cmp_lg_u64 vcc, 0
	s_cselect_b32 s10, 1, 0
	s_lshr_b32 s9, s11, 1
	s_or_b32 s10, s10, s9
	s_cmp_le_i32 s45, s15
	s_cselect_b32 s10, s10, 0
	s_cmp_ge_i32 s45, s40
	s_cselect_b32 s10, s10, 0
	s_or_b32 s12, s11, s10
	s_cmp_lg_u32 s41, 0
	s_cbranch_scc1 .Lat_xtop1
	s_branch .Lat_xexit

; #define LAS __attribute__((address_space(3)))
; template <bool SEL, bool GEN>
; DI void attn_step(const KF& kv, const int kb, const int t, const int lane, const bool selbit,
;                   const LAS float* tabh, const half8 (&q)[2][2], f32x4 (&O)[2][4], const float (&nR)[2], float (&l)[2]) {
;     ...
;   for (int hp = 0; hp < 2; ++hp) {
;     float nm = nR[hp];
;     if (SEL) nm = selbit ? nm : MASKV;
;     const f32x4 c0 = {nm, nm, nm, nm};
; DI void attn_phase(const Params& p, const int layer, const int wid_s) {
;     ...
;           LAS unsigned char* slotp = ring + (si % 3) * 8192;
;           KF kv;
; #pragma unroll
;           for (int kt = 0; kt < 2; ++kt)
; #pragma unroll
;             for (int ks = 0; ks < 2; ++ks) kv.k[kt][ks] = *(const LAS half8*)(slotp + kread[kt][ks]);
; #pragma unroll
;           for (int dt = 0; dt < 4; ++dt) kv.v[dt] = *(const LAS half8*)(slotp + vread[dt]);
;           if (br == 1) {
;             const bool bit = (selmask >> (kb >> 6)) & 1u;
.Lat_nogi_xt1:
	s_bitcmp1_b32 s12, 0
	s_cbranch_scc0 .Lat_xskip1
	ds_read_b128 v[96:99], v0 offset:8192
	ds_read_b128 v[92:95], v64 offset:8192
	ds_read_b128 v[88:91], v0 offset:10240
	ds_read_b128 v[84:87], v64 offset:10240
	s_lshr_b32 s10, s45, 6
	s_cmp_eq_u32 s10, s13
	s_cbranch_scc1 .Lat_cok_x1
	s_mov_b32 s13, s10
	v_bfe_u32 v66, v244, s10, 1
	v_cmp_ne_u32_e32 vcc, 0, v66
	s_nop 1
	v_cndmask_b32_e32 v128, v4, v242, vcc
	v_cndmask_b32_e32 v132, v4, v243, vcc
	v_cndmask_b32_e32 v129, v4, v242, vcc
	v_cndmask_b32_e32 v133, v4, v243, vcc
	v_cndmask_b32_e32 v130, v4, v242, vcc
	v_cndmask_b32_e32 v134, v4, v243, vcc
	v_cndmask_b32_e32 v131, v4, v242, vcc
	v_cndmask_b32_e32 v135, v4, v243, vcc

; #define MFMA16(a, b, c) __builtin_amdgcn_mfma_f32_16x16x32_f16((a), (b), (c), 0, 0, 0)
; #define RING_ISSUE(SI) do { int kbi = kb0 + (SI) * 32; if (kbi > kb_last) kbi = kb_last; const int slot = (SI) % 3; \
;           const h16* srcp = wave < 4 ? kbase + (size_t)kbi * LDH + k_src_off : vT + (size_t)(kbi >> 5) * 2048 + v_src_off; \
;           __builtin_amdgcn_global_load_lds((const unsigned*)srcp, (LAS unsigned*)(ring + slot * 8192 + stage_dst), 16, 0, 0); } while (0)
; template <bool SEL, bool GEN>
; DI void attn_step(const KF& kv, const int kb, const int t, const int lane, const bool selbit,
;                   const LAS float* tabh, const half8 (&q)[2][2], f32x4 (&O)[2][4], const float (&nR)[2], float (&l)[2]) {
;     ...
;       s[hp][kt] = MFMA16(kv.k[kt][0], q[hp][0], c0);
;       s[hp][kt] = MFMA16(kv.k[kt][1], q[hp][1], s[hp][kt]);
;     }
;   }
;   if (GEN) {
;     const int d0 = t - kb - fq * 4;
; #pragma unroll
;     for (int kt = 0; kt < 2; ++kt)
; #pragma unroll
;       for (int j = 0; j < 4; ++j) {
;         const int dist = d0 - (kt * 16 + j);
;         const bool bad = SEL ? (dist < 0) : ((unsigned)dist >= 512u);
;         const int ix = bad ? 130 : (dist > 128 ? 128 : dist);
; #pragma unroll
;         for (int hp = 0; hp < 2; ++hp) s[hp][kt][j] += tabh[hp * 132 + ix];
;       }
;   }
;   half8 pf[2];
; #pragma unroll
;   for (int hp = 0; hp < 2; ++hp) {
;     f32x4 p0, p1;
; #pragma unroll
;     for (int j = 0; j < 4; ++j) { p0[j] = __builtin_amdgcn_exp2f(s[hp][0][j]); p1[j] = __builtin_amdgcn_exp2f(s[hp][1][j]); }
;     l[hp] += ((p0[0] + p0[1]) + (p0[2] + p0[3])) + ((p1[0] + p1[1]) + (p1[2] + p1[3]));
;     pf[hp] = pack8(p0, p1);
;   }
; #pragma unroll
;   for (int dt = 0; dt < 4; ++dt)
; #pragma unroll
;     for (int hp = 0; hp < 2; ++hp) O[hp][dt] = MFMA16(kv.v[dt], pf[hp], O[hp][dt]);
; DI void attn_phase(const Params& p, const int layer, const int wid_s) {
;     ...
;         for (int si = 0; si < nsteps; ++si) {
;           asm volatile("s_waitcnt vmcnt(1) lgkmcnt(0)" ::: "memory");
;           __builtin_amdgcn_s_barrier();
;           asm volatile("" ::: "memory");
;           RING_ISSUE(si + 2);
;           const int kb = kb0 + si * 32;
;           if (kb > kmax_w || kb < lo_w) continue;
;           if (br == 1 && kb + 31 + 128 <= t0 && __ballot((selmask >> (kb >> 6)) & 1u) == 0ull) continue;
.Lat_noga_xa1:
	v_exp_f32_e32 v198, v100
	v_exp_f32_e32 v199, v101
	v_exp_f32_e32 v200, v102
	v_exp_f32_e32 v201, v103
	v_exp_f32_e32 v202, v104
	v_exp_f32_e32 v203, v105
	v_exp_f32_e32 v204, v106
	v_exp_f32_e32 v205, v107
	v_exp_f32_e32 v206, v108
	v_exp_f32_e32 v207, v109
	v_exp_f32_e32 v208, v110
	v_exp_f32_e32 v209, v111
	v_exp_f32_e32 v210, v112
	v_exp_f32_e32 v211, v113
	v_exp_f32_e32 v212, v114
	v_exp_f32_e32 v213, v115
	v_cvt_pkrtz_f16_f32 v120, v198, v199
	v_cvt_pkrtz_f16_f32 v121, v200, v201
	v_cvt_pkrtz_f16_f32 v122, v202, v203
	v_cvt_pkrtz_f16_f32 v123, v204, v205
	v_cvt_pkrtz_f16_f32 v124, v206, v207
	v_cvt_pkrtz_f16_f32 v125, v208, v209
	v_cvt_pkrtz_f16_f32 v126, v210, v211
	v_cvt_pkrtz_f16_f32 v127, v212, v213
	s_waitcnt lgkmcnt(0)
	s_and_b32 s44, s12, 2
	s_or_b32 s44, s44, 1
	v_mfma_f32_16x16x32_f16 v[100:103], v[96:99], v[8:11], v[128:131]
	s_add_i32 s8, s45, 64
	s_min_i32 s8, s8, s14
	s_mul_i32 s8, s8, s42
	s_mov_b32 s9, 0
	v_mfma_f32_16x16x32_f16 v[104:107], v[88:91], v[8:11], v[128:131]
	v_lshl_add_u64 v[238:239], v[240:241], 0, s[8:9]
	s_add_i32 m0, s43, s22
	s_nop 0
	global_load_lds_dwordx4 v[238:239], off
	v_mfma_f32_16x16x32_f16 v[108:111], v[96:99], v[16:19], v[132:135]
	s_add_i32 s43, s43, 0x2000
	s_cmp_eq_u32 s43, 0x1f880
	s_cselect_b32 s43, 0x20080, s43
	s_cmp_eq_u32 s43, 0x22080
	s_cselect_b32 s43, 0x19880, s43
	v_mfma_f32_16x16x32_f16 v[112:115], v[88:91], v[16:19], v[132:135]
	s_add_i32 s45, s45, 32
	s_add_i32 s41, s41, -1
	s_add_i32 s10, s45, 0x9f
	s_cmp_gt_i32 s10, s51
	v_mfma_f32_16x16x32_f16 v[100:103], v[92:95], v[12:15], v[100:103]
	s_cselect_b32 s11, 2, 0
	s_add_i32 s10, s45, 0x1f1
	s_cmp_le_i32 s10, s51
	s_cselect_b32 s10, 2, 0
	v_mfma_f32_16x16x32_f16 v[104:107], v[84:87], v[12:15], v[104:107]
	s_and_b32 s10, s10, s4
	s_or_b32 s11, s11, s10
	s_lshr_b32 s10, s45, 6
	v_bfe_u32 v66, v244, s10, 1
	v_cmp_ne_u32_e32 vcc, 0, v66
	v_mfma_f32_16x16x32_f16 v[108:111], v[92:95], v[20:23], v[108:111]
	s_cmp_lg_u64 vcc, 0
	s_cselect_b32 s10, 1, 0
	s_lshr_b32 s9, s11, 1
	s_or_b32 s10, s10, s9
	v_mfma_f32_16x16x32_f16 v[112:115], v[84:87], v[20:23], v[112:115]
	s_cmp_le_i32 s45, s15
	s_cselect_b32 s10, s10, 0
	s_cmp_ge_i32 s45, s40
	s_cselect_b32 s10, s10, 0
	s_or_b32 s12, s11, s10
	v_mfma_f32_16x16x32_f16 v[60:63], v[80:83], v[120:123], v[60:63]
	v_add_f32_e32 v214, v214, v198
	v_add_f32_e32 v215, v215, v199
	v_mfma_f32_16x16x32_f16 v[56:59], v[76:79], v[120:123], v[56:59]
	v_add_f32_e32 v216, v216, v200
	v_add_f32_e32 v217, v217, v201
	v_mfma_f32_16x16x32_f16 v[52:55], v[72:75], v[120:123], v[52:55]
	v_add_f32_e32 v214, v214, v202
	v_add_f32_e32 v215, v215, v203
	v_mfma_f32_16x16x32_f16 v[48:51], v[68:71], v[120:123], v[48:51]
	v_add_f32_e32 v216, v216, v204
	v_add_f32_e32 v217, v217, v205
	v_mfma_f32_16x16x32_f16 v[44:47], v[80:83], v[124:127], v[44:47]
	v_add_f32_e32 v218, v218, v206
	v_add_f32_e32 v219, v219, v207
	v_mfma_f32_16x16x32_f16 v[40:43], v[76:79], v[124:127], v[40:43]
	v_add_f32_e32 v220, v220, v208
	v_add_f32_e32 v221, v221, v209
	v_mfma_f32_16x16x32_f16 v[36:39], v[72:75], v[124:127], v[36:39]
	v_add_f32_e32 v218, v218, v210
	v_add_f32_e32 v219, v219, v211
	v_mfma_f32_16x16x32_f16 v[32:35], v[68:71], v[124:127], v[32:35]
	v_add_f32_e32 v220, v220, v212
	v_add_f32_e32 v221, v221, v213
	ds_read_b128 v[80:83], v65 offset:12288
	ds_read_b128 v[76:79], v65 offset:13312
	ds_read_b128 v[72:75], v65 offset:14336
	ds_read_b128 v[68:71], v65 offset:15360
	s_cmp_lg_u32 s41, 0
	s_cbranch_scc1 .Lat_xtop2
	s_branch .Lat_xexit
.Lat_xb1:
	s_waitcnt lgkmcnt(0)
	s_and_b32 s44, s12, 2
	s_or_b32 s44, s44, 1
	v_mfma_f32_16x16x32_f16 v[100:103], v[96:99], v[8:11], v[128:131]
	s_add_i32 s8, s45, 64
	s_min_i32 s8, s8, s14
	s_mul_i32 s8, s8, s42
	s_mov_b32 s9, 0
	v_mfma_f32_16x16x32_f16 v[104:107], v[88:91], v[8:11], v[128:131]
	v_lshl_add_u64 v[238:239], v[240:241], 0, s[8:9]
	s_add_i32 m0, s43, s22
	s_nop 0
	global_load_lds_dwordx4 v[238:239], off
	v_mfma_f32_16x16x32_f16 v[108:111], v[96:99], v[16:19], v[132:135]
	s_add_i32 s43, s43, 0x2000
	s_cmp_eq_u32 s43, 0x1f880
	s_cselect_b32 s43, 0x20080, s43
	s_cmp_eq_u32 s43, 0x22080
	s_cselect_b32 s43, 0x19880, s43
	v_mfma_f32_16x16x32_f16 v[112:115], v[88:91], v[16:19], v[132:135]
	s_add_i32 s45, s45, 32
	s_add_i32 s41, s41, -1
	s_add_i32 s10, s45, 0x9f
	s_cmp_gt_i32 s10, s51
	v_mfma_f32_16x16x32_f16 v[100:103], v[92:95], v[12:15], v[100:103]
	s_cselect_b32 s11, 2, 0
	s_add_i32 s10, s45, 0x1f1
	s_cmp_le_i32 s10, s51
	s_cselect_b32 s10, 2, 0
	v_mfma_f32_16x16x32_f16 v[104:107], v[84:87], v[12:15], v[104:107]
	s_and_b32 s10, s10, s4
	s_or_b32 s11, s11, s10
	s_lshr_b32 s10, s45, 6
	v_bfe_u32 v66, v244, s10, 1
	v_cmp_ne_u32_e32 vcc, 0, v66
	v_mfma_f32_16x16x32_f16 v[108:111], v[92:95], v[20:23], v[108:111]
	s_cmp_lg_u64 vcc, 0
	s_cselect_b32 s10, 1, 0
	s_lshr_b32 s9, s11, 1
	s_or_b32 s10, s10, s9
	v_mfma_f32_16x16x32_f16 v[112:115], v[84:87], v[20:23], v[112:115]
	s_cmp_le_i32 s45, s15
	s_cselect_b32 s10, s10, 0
	s_cmp_ge_i32 s45, s40
	s_cselect_b32 s10, s10, 0
	s_or_b32 s12, s11, s10
	ds_read_b128 v[80:83], v65 offset:12288
	ds_read_b128 v[76:79], v65 offset:13312
	ds_read_b128 v[72:75], v65 offset:14336
	ds_read_b128 v[68:71], v65 offset:15360
	s_cmp_lg_u32 s41, 0
	s_cbranch_scc1 .Lat_xtop2
	s_branch .Lat_xexit

; #define LAS __attribute__((address_space(3)))
; template <bool SEL, bool GEN>
; DI void attn_step(const KF& kv, const int kb, const int t, const int lane, const bool selbit,
;                   const LAS float* tabh, const half8 (&q)[2][2], f32x4 (&O)[2][4], const float (&nR)[2], float (&l)[2]) {
;     ...
;   for (int hp = 0; hp < 2; ++hp) {
;     float nm = nR[hp];
;     if (SEL) nm = selbit ? nm : MASKV;
;     const f32x4 c0 = {nm, nm, nm, nm};
; DI void attn_phase(const Params& p, const int layer, const int wid_s) {
;     ...
;           LAS unsigned char* slotp = ring + (si % 3) * 8192;
;           KF kv;
; #pragma unroll
;           for (int kt = 0; kt < 2; ++kt)
; #pragma unroll
;             for (int ks = 0; ks < 2; ++ks) kv.k[kt][ks] = *(const LAS half8*)(slotp + kread[kt][ks]);
; #pragma unroll
;           for (int dt = 0; dt < 4; ++dt) kv.v[dt] = *(const LAS half8*)(slotp + vread[dt]);
;           if (br == 1) {
;             const bool bit = (selmask >> (kb >> 6)) & 1u;
.Lat_nogi_xt2:
	s_bitcmp1_b32 s12, 0
	s_cbranch_scc0 .Lat_xskip2
	ds_read_b128 v[96:99], v0 offset:16384
	ds_read_b128 v[92:95], v64 offset:16384
	ds_read_b128 v[88:91], v0 offset:18432
	ds_read_b128 v[84:87], v64 offset:18432
	s_lshr_b32 s10, s45, 6
	s_cmp_eq_u32 s10, s13
	s_cbranch_scc1 .Lat_cok_x2
	s_mov_b32 s13, s10
	v_bfe_u32 v66, v244, s10, 1
	v_cmp_ne_u32_e32 vcc, 0, v66
	s_nop 1
	v_cndmask_b32_e32 v128, v4, v242, vcc
	v_cndmask_b32_e32 v132, v4, v243, vcc
	v_cndmask_b32_e32 v129, v4, v242, vcc
	v_cndmask_b32_e32 v133, v4, v243, vcc
	v_cndmask_b32_e32 v130, v4, v242, vcc
	v_cndmask_b32_e32 v134, v4, v243, vcc
	v_cndmask_b32_e32 v131, v4, v242, vcc
	v_cndmask_b32_e32 v135, v4, v243, vcc

; #define MFMA16(a, b, c) __builtin_amdgcn_mfma_f32_16x16x32_f16((a), (b), (c), 0, 0, 0)
; #define RING_ISSUE(SI) do { int kbi = kb0 + (SI) * 32; if (kbi > kb_last) kbi = kb_last; const int slot = (SI) % 3; \
;           const h16* srcp = wave < 4 ? kbase + (size_t)kbi * LDH + k_src_off : vT + (size_t)(kbi >> 5) * 2048 + v_src_off; \
;           __builtin_amdgcn_global_load_lds((const unsigned*)srcp, (LAS unsigned*)(ring + slot * 8192 + stage_dst), 16, 0, 0); } while (0)
; template <bool SEL, bool GEN>
; DI void attn_step(const KF& kv, const int kb, const int t, const int lane, const bool selbit,
;                   const LAS float* tabh, const half8 (&q)[2][2], f32x4 (&O)[2][4], const float (&nR)[2], float (&l)[2]) {
;     ...
;       s[hp][kt] = MFMA16(kv.k[kt][0], q[hp][0], c0);
;       s[hp][kt] = MFMA16(kv.k[kt][1], q[hp][1], s[hp][kt]);
;     }
;   }
;   if (GEN) {
;     const int d0 = t - kb - fq * 4;
; #pragma unroll
;     for (int kt = 0; kt < 2; ++kt)
; #pragma unroll
;       for (int j = 0; j < 4; ++j) {
;         const int dist = d0 - (kt * 16 + j);
;         const bool bad = SEL ? (dist < 0) : ((unsigned)dist >= 512u);
;         const int ix = bad ? 130 : (dist > 128 ? 128 : dist);
; #pragma unroll
;         for (int hp = 0; hp < 2; ++hp) s[hp][kt][j] += tabh[hp * 132 + ix];
;       }
;   }
;   half8 pf[2];
; #pragma unroll
;   for (int hp = 0; hp < 2; ++hp) {
;     f32x4 p0, p1;
; #pragma unroll
;     for (int j = 0; j < 4; ++j) { p0[j] = __builtin_amdgcn_exp2f(s[hp][0][j]); p1[j] = __builtin_amdgcn_exp2f(s[hp][1][j]); }
;     l[hp] += ((p0[0] + p0[1]) + (p0[2] + p0[3])) + ((p1[0] + p1[1]) + (p1[2] + p1[3]));
;     pf[hp] = pack8(p0, p1);
;   }
; #pragma unroll
;   for (int dt = 0; dt < 4; ++dt)
; #pragma unroll
;     for (int hp = 0; hp < 2; ++hp) O[hp][dt] = MFMA16(kv.v[dt], pf[hp], O[hp][dt]);
; DI void attn_phase(const Params& p, const int layer, const int wid_s) {
;     ...
;         for (int si = 0; si < nsteps; ++si) {
;           asm volatile("s_waitcnt vmcnt(1) lgkmcnt(0)" ::: "memory");
;           __builtin_amdgcn_s_barrier();
;           asm volatile("" ::: "memory");
;           RING_ISSUE(si + 2);
;           const int kb = kb0 + si * 32;
;           if (kb > kmax_w || kb < lo_w) continue;
;           if (br == 1 && kb + 31 + 128 <= t0 && __ballot((selmask >> (kb >> 6)) & 1u) == 0ull) continue;
.Lat_noga_xa2:
	v_exp_f32_e32 v198, v100
	v_exp_f32_e32 v199, v101
	v_exp_f32_e32 v200, v102
	v_exp_f32_e32 v201, v103
	v_exp_f32_e32 v202, v104
	v_exp_f32_e32 v203, v105
	v_exp_f32_e32 v204, v106
	v_exp_f32_e32 v205, v107
	v_exp_f32_e32 v206, v108
	v_exp_f32_e32 v207, v109
	v_exp_f32_e32 v208, v110
	v_exp_f32_e32 v209, v111
	v_exp_f32_e32 v210, v112
	v_exp_f32_e32 v211, v113
	v_exp_f32_e32 v212, v114
	v_exp_f32_e32 v213, v115
	v_cvt_pkrtz_f16_f32 v120, v198, v199
	v_cvt_pkrtz_f16_f32 v121, v200, v201
	v_cvt_pkrtz_f16_f32 v122, v202, v203
	v_cvt_pkrtz_f16_f32 v123, v204, v205
	v_cvt_pkrtz_f16_f32 v124, v206, v207
	v_cvt_pkrtz_f16_f32 v125, v208, v209
	v_cvt_pkrtz_f16_f32 v126, v210, v211
	v_cvt_pkrtz_f16_f32 v127, v212, v213
	s_waitcnt lgkmcnt(0)
	s_and_b32 s44, s12, 2
	s_or_b32 s44, s44, 1
	v_mfma_f32_16x16x32_f16 v[100:103], v[96:99], v[8:11], v[128:131]
	s_add_i32 s8, s45, 64
	s_min_i32 s8, s8, s14
	s_mul_i32 s8, s8, s42
	s_mov_b32 s9, 0
	v_mfma_f32_16x16x32_f16 v[104:107], v[88:91], v[8:11], v[128:131]
	v_lshl_add_u64 v[238:239], v[240:241], 0, s[8:9]
	s_add_i32 m0, s43, s22
	s_nop 0
	global_load_lds_dwordx4 v[238:239], off
	v_mfma_f32_16x16x32_f16 v[108:111], v[96:99], v[16:19], v[132:135]
	s_add_i32 s43, s43, 0x2000
	s_cmp_eq_u32 s43, 0x1f880
	s_cselect_b32 s43, 0x20080, s43
	s_cmp_eq_u32 s43, 0x22080
	s_cselect_b32 s43, 0x19880, s43
	v_mfma_f32_16x16x32_f16 v[112:115], v[88:91], v[16:19], v[132:135]
	s_add_i32 s45, s45, 32
	s_add_i32 s41, s41, -1
	s_add_i32 s10, s45, 0x9f
	s_cmp_gt_i32 s10, s51
	v_mfma_f32_16x16x32_f16 v[100:103], v[92:95], v[12:15], v[100:103]
	s_cselect_b32 s11, 2, 0
	s_add_i32 s10, s45, 0x1f1
	s_cmp_le_i32 s10, s51
	s_cselect_b32 s10, 2, 0
	v_mfma_f32_16x16x32_f16 v[104:107], v[84:87], v[12:15], v[104:107]
	s_and_b32 s10, s10, s4
	s_or_b32 s11, s11, s10
	s_lshr_b32 s10, s45, 6
	v_bfe_u32 v66, v244, s10, 1
	v_cmp_ne_u32_e32 vcc, 0, v66
	v_mfma_f32_16x16x32_f16 v[108:111], v[92:95], v[20:23], v[108:111]
	s_cmp_lg_u64 vcc, 0
	s_cselect_b32 s10, 1, 0
	s_lshr_b32 s9, s11, 1
	s_or_b32 s10, s10, s9
	v_mfma_f32_16x16x32_f16 v[112:115], v[84:87], v[20:23], v[112:115]
	s_cmp_le_i32 s45, s15
	s_cselect_b32 s10, s10, 0
	s_cmp_ge_i32 s45, s40
	s_cselect_b32 s10, s10, 0
	s_or_b32 s12, s11, s10
	v_mfma_f32_16x16x32_f16 v[60:63], v[80:83], v[120:123], v[60:63]
	v_add_f32_e32 v214, v214, v198
	v_add_f32_e32 v215, v215, v199
	v_mfma_f32_16x16x32_f16 v[56:59], v[76:79], v[120:123], v[56:59]
	v_add_f32_e32 v216, v216, v200
	v_add_f32_e32 v217, v217, v201
	v_mfma_f32_16x16x32_f16 v[52:55], v[72:75], v[120:123], v[52:55]
	v_add_f32_e32 v214, v214, v202
	v_add_f32_e32 v215, v215, v203
	v_mfma_f32_16x16x32_f16 v[48:51], v[68:71], v[120:123], v[48:51]
	v_add_f32_e32 v216, v216, v204
	v_add_f32_e32 v217, v217, v205
	v_mfma_f32_16x16x32_f16 v[44:47], v[80:83], v[124:127], v[44:47]
	v_add_f32_e32 v218, v218, v206
	v_add_f32_e32 v219, v219, v207
	v_mfma_f32_16x16x32_f16 v[40:43], v[76:79], v[124:127], v[40:43]
	v_add_f32_e32 v220, v220, v208
	v_add_f32_e32 v221, v221, v209
	v_mfma_f32_16x16x32_f16 v[36:39], v[72:75], v[124:127], v[36:39]
	v_add_f32_e32 v218, v218, v210
	v_add_f32_e32 v219, v219, v211
	v_mfma_f32_16x16x32_f16 v[32:35], v[68:71], v[124:127], v[32:35]
	v_add_f32_e32 v220, v220, v212
	v_add_f32_e32 v221, v221, v213
	ds_read_b128 v[80:83], v65 offset:20480
	ds_read_b128 v[76:79], v65 offset:21504
	ds_read_b128 v[72:75], v65 offset:22528
	ds_read_b128 v[68:71], v65 offset:23552
	s_cmp_lg_u32 s41, 0
	s_cbranch_scc1 .Lat_xtop3
	s_branch .Lat_xexit
.Lat_xb2:
	s_waitcnt lgkmcnt(0)
	s_and_b32 s44, s12, 2
	s_or_b32 s44, s44, 1
	v_mfma_f32_16x16x32_f16 v[100:103], v[96:99], v[8:11], v[128:131]
	s_add_i32 s8, s45, 64
	s_min_i32 s8, s8, s14
	s_mul_i32 s8, s8, s42
	s_mov_b32 s9, 0
	v_mfma_f32_16x16x32_f16 v[104:107], v[88:91], v[8:11], v[128:131]
	v_lshl_add_u64 v[238:239], v[240:241], 0, s[8:9]
	s_add_i32 m0, s43, s22
	s_nop 0
	global_load_lds_dwordx4 v[238:239], off
	v_mfma_f32_16x16x32_f16 v[108:111], v[96:99], v[16:19], v[132:135]
	s_add_i32 s43, s43, 0x2000
	s_cmp_eq_u32 s43, 0x1f880
	s_cselect_b32 s43, 0x20080, s43
	s_cmp_eq_u32 s43, 0x22080
	s_cselect_b32 s43, 0x19880, s43
	v_mfma_f32_16x16x32_f16 v[112:115], v[88:91], v[16:19], v[132:135]
	s_add_i32 s45, s45, 32
	s_add_i32 s41, s41, -1
	s_add_i32 s10, s45, 0x9f
	s_cmp_gt_i32 s10, s51
	v_mfma_f32_16x16x32_f16 v[100:103], v[92:95], v[12:15], v[100:103]
	s_cselect_b32 s11, 2, 0
	s_add_i32 s10, s45, 0x1f1
	s_cmp_le_i32 s10, s51
	s_cselect_b32 s10, 2, 0
	v_mfma_f32_16x16x32_f16 v[104:107], v[84:87], v[12:15], v[104:107]
	s_and_b32 s10, s10, s4
	s_or_b32 s11, s11, s10
	s_lshr_b32 s10, s45, 6
	v_bfe_u32 v66, v244, s10, 1
	v_cmp_ne_u32_e32 vcc, 0, v66
	v_mfma_f32_16x16x32_f16 v[108:111], v[92:95], v[20:23], v[108:111]
	s_cmp_lg_u64 vcc, 0
	s_cselect_b32 s10, 1, 0
	s_lshr_b32 s9, s11, 1
	s_or_b32 s10, s10, s9
	v_mfma_f32_16x16x32_f16 v[112:115], v[84:87], v[20:23], v[112:115]
	s_cmp_le_i32 s45, s15
	s_cselect_b32 s10, s10, 0
	s_cmp_ge_i32 s45, s40
	s_cselect_b32 s10, s10, 0
	s_or_b32 s12, s11, s10
	ds_read_b128 v[80:83], v65 offset:20480
	ds_read_b128 v[76:79], v65 offset:21504
	ds_read_b128 v[72:75], v65 offset:22528
	ds_read_b128 v[68:71], v65 offset:23552
	s_cmp_lg_u32 s41, 0
	s_cbranch_scc1 .Lat_xtop3
	s_branch .Lat_xexit

; #define LAS __attribute__((address_space(3)))
; template <bool SEL, bool GEN>
; DI void attn_step(const KF& kv, const int kb, const int t, const int lane, const bool selbit,
;                   const LAS float* tabh, const half8 (&q)[2][2], f32x4 (&O)[2][4], const float (&nR)[2], float (&l)[2]) {
;     ...
;   for (int hp = 0; hp < 2; ++hp) {
;     float nm = nR[hp];
;     if (SEL) nm = selbit ? nm : MASKV;
;     const f32x4 c0 = {nm, nm, nm, nm};
; DI void attn_phase(const Params& p, const int layer, const int wid_s) {
;     ...
;           LAS unsigned char* slotp = ring + (si % 3) * 8192;
;           KF kv;
; #pragma unroll
;           for (int kt = 0; kt < 2; ++kt)
; #pragma unroll
;             for (int ks = 0; ks < 2; ++ks) kv.k[kt][ks] = *(const LAS half8*)(slotp + kread[kt][ks]);
; #pragma unroll
;           for (int dt = 0; dt < 4; ++dt) kv.v[dt] = *(const LAS half8*)(slotp + vread[dt]);
;           if (br == 1) {
;             const bool bit = (selmask >> (kb >> 6)) & 1u;
.Lat_nogi_xt3:
	s_bitcmp1_b32 s12, 0
	s_cbranch_scc0 .Lat_xskip3
	ds_read_b128 v[96:99], v0 offset:26624
	ds_read_b128 v[92:95], v64 offset:26624
	ds_read_b128 v[88:91], v0 offset:28672
	ds_read_b128 v[84:87], v64 offset:28672
	s_lshr_b32 s10, s45, 6
	s_cmp_eq_u32 s10, s13
	s_cbranch_scc1 .Lat_cok_x3
	s_mov_b32 s13, s10
	v_bfe_u32 v66, v244, s10, 1
	v_cmp_ne_u32_e32 vcc, 0, v66
	s_nop 1
	v_cndmask_b32_e32 v128, v4, v242, vcc
	v_cndmask_b32_e32 v132, v4, v243, vcc
	v_cndmask_b32_e32 v129, v4, v242, vcc
	v_cndmask_b32_e32 v133, v4, v243, vcc
	v_cndmask_b32_e32 v130, v4, v242, vcc
	v_cndmask_b32_e32 v134, v4, v243, vcc
	v_cndmask_b32_e32 v131, v4, v242, vcc
	v_cndmask_b32_e32 v135, v4, v243, vcc

; #define MFMA16(a, b, c) __builtin_amdgcn_mfma_f32_16x16x32_f16((a), (b), (c), 0, 0, 0)
; #define RING_ISSUE(SI) do { int kbi = kb0 + (SI) * 32; if (kbi > kb_last) kbi = kb_last; const int slot = (SI) % 3; \
;           const h16* srcp = wave < 4 ? kbase + (size_t)kbi * LDH + k_src_off : vT + (size_t)(kbi >> 5) * 2048 + v_src_off; \
;           __builtin_amdgcn_global_load_lds((const unsigned*)srcp, (LAS unsigned*)(ring + slot * 8192 + stage_dst), 16, 0, 0); } while (0)
; template <bool SEL, bool GEN>
; DI void attn_step(const KF& kv, const int kb, const int t, const int lane, const bool selbit,
;                   const LAS float* tabh, const half8 (&q)[2][2], f32x4 (&O)[2][4], const float (&nR)[2], float (&l)[2]) {
;     ...
;       s[hp][kt] = MFMA16(kv.k[kt][0], q[hp][0], c0);
;       s[hp][kt] = MFMA16(kv.k[kt][1], q[hp][1], s[hp][kt]);
;     }
;   }
;   if (GEN) {
;     const int d0 = t - kb - fq * 4;
; #pragma unroll
;     for (int kt = 0; kt < 2; ++kt)
; #pragma unroll
;       for (int j = 0; j < 4; ++j) {
;         const int dist = d0 - (kt * 16 + j);
;         const bool bad = SEL ? (dist < 0) : ((unsigned)dist >= 512u);
;         const int ix = bad ? 130 : (dist > 128 ? 128 : dist);
; #pragma unroll
;         for (int hp = 0; hp < 2; ++hp) s[hp][kt][j] += tabh[hp * 132 + ix];
;       }
;   }
;   half8 pf[2];
; #pragma unroll
;   for (int hp = 0; hp < 2; ++hp) {
;     f32x4 p0, p1;
; #pragma unroll
;     for (int j = 0; j < 4; ++j) { p0[j] = __builtin_amdgcn_exp2f(s[hp][0][j]); p1[j] = __builtin_amdgcn_exp2f(s[hp][1][j]); }
;     l[hp] += ((p0[0] + p0[1]) + (p0[2] + p0[3])) + ((p1[0] + p1[1]) + (p1[2] + p1[3]));
;     pf[hp] = pack8(p0, p1);
;   }
; #pragma unroll
;   for (int dt = 0; dt < 4; ++dt)
; #pragma unroll
;     for (int hp = 0; hp < 2; ++hp) O[hp][dt] = MFMA16(kv.v[dt], pf[hp], O[hp][dt]);
; DI void attn_phase(const Params& p, const int layer, const int wid_s) {
;     ...
;         for (int si = 0; si < nsteps; ++si) {
;           asm volatile("s_waitcnt vmcnt(1) lgkmcnt(0)" ::: "memory");
;           __builtin_amdgcn_s_barrier();
;           asm volatile("" ::: "memory");
;           RING_ISSUE(si + 2);
;           const int kb = kb0 + si * 32;
;           if (kb > kmax_w || kb < lo_w) continue;
;           if (br == 1 && kb + 31 + 128 <= t0 && __ballot((selmask >> (kb >> 6)) & 1u) == 0ull) continue;
.Lat_noga_xa3:
	v_exp_f32_e32 v198, v100
	v_exp_f32_e32 v199, v101
	v_exp_f32_e32 v200, v102
	v_exp_f32_e32 v201, v103
	v_exp_f32_e32 v202, v104
	v_exp_f32_e32 v203, v105
	v_exp_f32_e32 v204, v106
	v_exp_f32_e32 v205, v107
	v_exp_f32_e32 v206, v108
	v_exp_f32_e32 v207, v109
	v_exp_f32_e32 v208, v110
	v_exp_f32_e32 v209, v111
	v_exp_f32_e32 v210, v112
	v_exp_f32_e32 v211, v113
	v_exp_f32_e32 v212, v114
	v_exp_f32_e32 v213, v115
	v_cvt_pkrtz_f16_f32 v120, v198, v199
	v_cvt_pkrtz_f16_f32 v121, v200, v201
	v_cvt_pkrtz_f16_f32 v122, v202, v203
	v_cvt_pkrtz_f16_f32 v123, v204, v205
	v_cvt_pkrtz_f16_f32 v124, v206, v207
	v_cvt_pkrtz_f16_f32 v125, v208, v209
	v_cvt_pkrtz_f16_f32 v126, v210, v211
	v_cvt_pkrtz_f16_f32 v127, v212, v213
	s_waitcnt lgkmcnt(0)
	s_and_b32 s44, s12, 2
	s_or_b32 s44, s44, 1
	v_mfma_f32_16x16x32_f16 v[100:103], v[96:99], v[8:11], v[128:131]
	s_add_i32 s8, s45, 64
	s_min_i32 s8, s8, s14
	s_mul_i32 s8, s8, s42
	s_mov_b32 s9, 0
	v_mfma_f32_16x16x32_f16 v[104:107], v[88:91], v[8:11], v[128:131]
	v_lshl_add_u64 v[238:239], v[240:241], 0, s[8:9]
	s_add_i32 m0, s43, s22
	s_nop 0
	global_load_lds_dwordx4 v[238:239], off
	v_mfma_f32_16x16x32_f16 v[108:111], v[96:99], v[16:19], v[132:135]
	s_add_i32 s43, s43, 0x2000
	s_cmp_eq_u32 s43, 0x1f880
	s_cselect_b32 s43, 0x20080, s43
	s_cmp_eq_u32 s43, 0x22080
	s_cselect_b32 s43, 0x19880, s43
	v_mfma_f32_16x16x32_f16 v[112:115], v[88:91], v[16:19], v[132:135]
	s_add_i32 s45, s45, 32
	s_add_i32 s41, s41, -1
	s_add_i32 s10, s45, 0x9f
	s_cmp_gt_i32 s10, s51
	v_mfma_f32_16x16x32_f16 v[100:103], v[92:95], v[12:15], v[100:103]
	s_cselect_b32 s11, 2, 0
	s_add_i32 s10, s45, 0x1f1
	s_cmp_le_i32 s10, s51
	s_cselect_b32 s10, 2, 0
	v_mfma_f32_16x16x32_f16 v[104:107], v[84:87], v[12:15], v[104:107]
	s_and_b32 s10, s10, s4
	s_or_b32 s11, s11, s10
	s_lshr_b32 s10, s45, 6
	v_bfe_u32 v66, v244, s10, 1
	v_cmp_ne_u32_e32 vcc, 0, v66
	v_mfma_f32_16x16x32_f16 v[108:111], v[92:95], v[20:23], v[108:111]
	s_cmp_lg_u64 vcc, 0
	s_cselect_b32 s10, 1, 0
	s_lshr_b32 s9, s11, 1
	s_or_b32 s10, s10, s9
	v_mfma_f32_16x16x32_f16 v[112:115], v[84:87], v[20:23], v[112:115]
	s_cmp_le_i32 s45, s15
	s_cselect_b32 s10, s10, 0
	s_cmp_ge_i32 s45, s40
	s_cselect_b32 s10, s10, 0
	s_or_b32 s12, s11, s10
	v_mfma_f32_16x16x32_f16 v[60:63], v[80:83], v[120:123], v[60:63]
	v_add_f32_e32 v214, v214, v198
	v_add_f32_e32 v215, v215, v199
	v_mfma_f32_16x16x32_f16 v[56:59], v[76:79], v[120:123], v[56:59]
	v_add_f32_e32 v216, v216, v200
	v_add_f32_e32 v217, v217, v201
	v_mfma_f32_16x16x32_f16 v[52:55], v[72:75], v[120:123], v[52:55]
	v_add_f32_e32 v214, v214, v202
	v_add_f32_e32 v215, v215, v203
	v_mfma_f32_16x16x32_f16 v[48:51], v[68:71], v[120:123], v[48:51]
	v_add_f32_e32 v216, v216, v204
	v_add_f32_e32 v217, v217, v205
	v_mfma_f32_16x16x32_f16 v[44:47], v[80:83], v[124:127], v[44:47]
	v_add_f32_e32 v218, v218, v206
	v_add_f32_e32 v219, v219, v207
	v_mfma_f32_16x16x32_f16 v[40:43], v[76:79], v[124:127], v[40:43]
	v_add_f32_e32 v220, v220, v208
	v_add_f32_e32 v221, v221, v209
	v_mfma_f32_16x16x32_f16 v[36:39], v[72:75], v[124:127], v[36:39]
	v_add_f32_e32 v218, v218, v210
	v_add_f32_e32 v219, v219, v211
	v_mfma_f32_16x16x32_f16 v[32:35], v[68:71], v[124:127], v[32:35]
	v_add_f32_e32 v220, v220, v212
	v_add_f32_e32 v221, v221, v213
	ds_read_b128 v[80:83], v65 offset:30720
	ds_read_b128 v[76:79], v65 offset:31744
	ds_read_b128 v[72:75], v65 offset:32768
	ds_read_b128 v[68:71], v65 offset:33792
	s_cmp_lg_u32 s41, 0
	s_cbranch_scc1 .Lat_xtop
	s_branch .Lat_xexit
.Lat_xb3:
	s_waitcnt lgkmcnt(0)
	s_and_b32 s44, s12, 2
	s_or_b32 s44, s44, 1
	v_mfma_f32_16x16x32_f16 v[100:103], v[96:99], v[8:11], v[128:131]
	s_add_i32 s8, s45, 64
	s_min_i32 s8, s8, s14
	s_mul_i32 s8, s8, s42
	s_mov_b32 s9, 0
	v_mfma_f32_16x16x32_f16 v[104:107], v[88:91], v[8:11], v[128:131]
	v_lshl_add_u64 v[238:239], v[240:241], 0, s[8:9]
	s_add_i32 m0, s43, s22
	s_nop 0
	global_load_lds_dwordx4 v[238:239], off
	v_mfma_f32_16x16x32_f16 v[108:111], v[96:99], v[16:19], v[132:135]
	s_add_i32 s43, s43, 0x2000
	s_cmp_eq_u32 s43, 0x1f880
	s_cselect_b32 s43, 0x20080, s43
	s_cmp_eq_u32 s43, 0x22080
	s_cselect_b32 s43, 0x19880, s43
	v_mfma_f32_16x16x32_f16 v[112:115], v[88:91], v[16:19], v[132:135]
	s_add_i32 s45, s45, 32
	s_add_i32 s41, s41, -1
	s_add_i32 s10, s45, 0x9f
	s_cmp_gt_i32 s10, s51
	v_mfma_f32_16x16x32_f16 v[100:103], v[92:95], v[12:15], v[100:103]
	s_cselect_b32 s11, 2, 0
	s_add_i32 s10, s45, 0x1f1
	s_cmp_le_i32 s10, s51
	s_cselect_b32 s10, 2, 0
	v_mfma_f32_16x16x32_f16 v[104:107], v[84:87], v[12:15], v[104:107]
	s_and_b32 s10, s10, s4
	s_or_b32 s11, s11, s10
	s_lshr_b32 s10, s45, 6
	v_bfe_u32 v66, v244, s10, 1
	v_cmp_ne_u32_e32 vcc, 0, v66
	v_mfma_f32_16x16x32_f16 v[108:111], v[92:95], v[20:23], v[108:111]
	s_cmp_lg_u64 vcc, 0
	s_cselect_b32 s10, 1, 0
	s_lshr_b32 s9, s11, 1
	s_or_b32 s10, s10, s9
	v_mfma_f32_16x16x32_f16 v[112:115], v[84:87], v[20:23], v[112:115]
	s_cmp_le_i32 s45, s15
	s_cselect_b32 s10, s10, 0
	s_cmp_ge_i32 s45, s40
	s_cselect_b32 s10, s10, 0
	s_or_b32 s12, s11, s10
	ds_read_b128 v[80:83], v65 offset:30720
	ds_read_b128 v[76:79], v65 offset:31744
	ds_read_b128 v[72:75], v65 offset:32768
	ds_read_b128 v[68:71], v65 offset:33792
	s_cmp_lg_u32 s41, 0
	s_cbranch_scc1 .Lat_xtop
	s_branch .Lat_xexit

; #define MFMA16(a, b, c) __builtin_amdgcn_mfma_f32_16x16x32_f16((a), (b), (c), 0, 0, 0)
; #define LAS __attribute__((address_space(3)))
; template <bool SEL, bool GEN>
; DI void attn_step(const KF& kv, const int kb, const int t, const int lane, const bool selbit,
;                   const LAS float* tabh, const half8 (&q)[2][2], f32x4 (&O)[2][4], const float (&nR)[2], float (&l)[2]) {
;     ...
;       s[hp][kt] = MFMA16(kv.k[kt][0], q[hp][0], c0);
;       s[hp][kt] = MFMA16(kv.k[kt][1], q[hp][1], s[hp][kt]);
;     }
;   }
;   if (GEN) {
;     const int d0 = t - kb - fq * 4;
; #pragma unroll
;     for (int kt = 0; kt < 2; ++kt)
; #pragma unroll
;       for (int j = 0; j < 4; ++j) {
;         const int dist = d0 - (kt * 16 + j);
;         const bool bad = SEL ? (dist < 0) : ((unsigned)dist >= 512u);
;         const int ix = bad ? 130 : (dist > 128 ? 128 : dist);
; #pragma unroll
;         for (int hp = 0; hp < 2; ++hp) s[hp][kt][j] += tabh[hp * 132 + ix];
;     ...
; #pragma unroll
;   for (int dt = 0; dt < 4; ++dt)
; #pragma unroll
;     for (int hp = 0; hp < 2; ++hp) O[hp][dt] = MFMA16(kv.v[dt], pf[hp], O[hp][dt]);
; DI void attn_phase(const Params& p, const int layer, const int wid_s) {
;     ...
;           LAS unsigned char* slotp = ring + (si % 3) * 8192;
;           KF kv;
; #pragma unroll
;           for (int kt = 0; kt < 2; ++kt)
; #pragma unroll
;             for (int ks = 0; ks < 2; ++ks) kv.k[kt][ks] = *(const LAS half8*)(slotp + kread[kt][ks]);
; #pragma unroll
;           for (int dt = 0; dt < 4; ++dt) kv.v[dt] = *(const LAS half8*)(slotp + vread[dt]);
;           if (br == 1) {
;             const bool bit = (selmask >> (kb >> 6)) & 1u;
;             if (kb + 31 + 128 <= t0) attn_step<true, false>(kv, kb, t, lane, bit, tabh, q, O, nRs, l);
;             else attn_step<true, true>(kv, kb, t, lane, bit, tabh, q, O, nRs, l);
.Lat_nogi_yt0:
	ds_read_b128 v[96:99], v0 offset:0
	ds_read_b128 v[92:95], v64 offset:0
	ds_read_b128 v[88:91], v0 offset:2048
	ds_read_b128 v[84:87], v64 offset:2048
	s_lshr_b32 s10, s45, 6
	s_cmp_eq_u32 s10, s13
	s_cbranch_scc1 .Lat_cok_y0
	s_mov_b32 s13, s10
	v_bfe_u32 v66, v244, s10, 1
	v_cmp_ne_u32_e32 vcc, 0, v66
	s_nop 1
	v_cndmask_b32_e32 v128, v4, v242, vcc
	v_cndmask_b32_e32 v132, v4, v243, vcc
	v_cndmask_b32_e32 v129, v4, v242, vcc
	v_cndmask_b32_e32 v133, v4, v243, vcc
	v_cndmask_b32_e32 v130, v4, v242, vcc
	v_cndmask_b32_e32 v134, v4, v243, vcc
	v_cndmask_b32_e32 v131, v4, v242, vcc
	v_cndmask_b32_e32 v135, v4, v243, vcc
.Lat_cok_y0:
	s_bitcmp1_b32 s44, 0
	s_cbranch_scc0 .Lat_yb0
	s_waitcnt lgkmcnt(4)
	v_mfma_f32_16x16x32_f16 v[60:63], v[80:83], v[120:123], v[60:63]
	v_add_f32_e32 v214, v214, v198
	v_add_f32_e32 v215, v215, v199
	v_add_f32_e32 v216, v216, v200
	v_mfma_f32_16x16x32_f16 v[56:59], v[76:79], v[120:123], v[56:59]
	v_add_f32_e32 v217, v217, v201
	v_add_f32_e32 v214, v214, v202
	v_add_f32_e32 v215, v215, v203
	v_mfma_f32_16x16x32_f16 v[52:55], v[72:75], v[120:123], v[52:55]
	v_add_f32_e32 v216, v216, v204
	v_add_f32_e32 v217, v217, v205
	v_add_f32_e32 v218, v218, v206
	v_mfma_f32_16x16x32_f16 v[48:51], v[68:71], v[120:123], v[48:51]
	v_add_f32_e32 v219, v219, v207
	v_add_f32_e32 v220, v220, v208
	v_add_f32_e32 v221, v221, v209
	v_mfma_f32_16x16x32_f16 v[44:47], v[80:83], v[124:127], v[44:47]
	v_add_f32_e32 v218, v218, v210
	v_add_f32_e32 v219, v219, v211
	v_add_f32_e32 v220, v220, v212
	v_mfma_f32_16x16x32_f16 v[40:43], v[76:79], v[124:127], v[40:43]
	v_add_f32_e32 v221, v221, v213
	s_add_i32 s8, s45, 64
	s_min_i32 s8, s8, s14
	v_mfma_f32_16x16x32_f16 v[36:39], v[72:75], v[124:127], v[36:39]
	s_mul_i32 s8, s8, s42
	s_mov_b32 s9, 0
	v_lshl_add_u64 v[238:239], v[240:241], 0, s[8:9]
	v_mfma_f32_16x16x32_f16 v[32:35], v[68:71], v[124:127], v[32:35]
	s_add_i32 m0, s43, s22
	s_nop 0
	global_load_lds_dwordx4 v[238:239], off
	s_waitcnt lgkmcnt(0)
	s_and_b32 s44, s12, 2
	s_or_b32 s44, s44, 1
	v_mfma_f32_16x16x32_f16 v[100:103], v[96:99], v[8:11], v[128:131]
	s_add_i32 s43, s43, 0x2000
	s_cmp_eq_u32 s43, 0x1f880
	s_cselect_b32 s43, 0x20080, s43
	v_mfma_f32_16x16x32_f16 v[104:107], v[88:91], v[8:11], v[128:131]
	s_cmp_eq_u32 s43, 0x22080
	s_cselect_b32 s43, 0x19880, s43
	s_add_i32 s45, s45, 32
	v_mfma_f32_16x16x32_f16 v[108:111], v[96:99], v[16:19], v[132:135]
	s_add_i32 s41, s41, -1
	s_add_i32 s10, s45, 0x9f
	s_cmp_gt_i32 s10, s51
	s_cselect_b32 s11, 2, 0
	v_mfma_f32_16x16x32_f16 v[112:115], v[88:91], v[16:19], v[132:135]
	s_add_i32 s10, s45, 0x1f1
	s_cmp_le_i32 s10, s51
	s_cselect_b32 s10, 2, 0
	v_mfma_f32_16x16x32_f16 v[100:103], v[92:95], v[12:15], v[100:103]
	s_and_b32 s10, s10, s4
	s_or_b32 s11, s11, s10
	s_lshr_b32 s10, s45, 6
	v_mfma_f32_16x16x32_f16 v[104:107], v[84:87], v[12:15], v[104:107]
	v_bfe_u32 v66, v244, s10, 1
	v_cmp_ne_u32_e32 vcc, 0, v66
	s_cmp_lg_u64 vcc, 0
	s_cselect_b32 s10, 1, 0
	v_mfma_f32_16x16x32_f16 v[108:111], v[92:95], v[20:23], v[108:111]
	s_lshr_b32 s9, s11, 1
	s_or_b32 s10, s10, s9
	s_cmp_le_i32 s45, s15
	v_mfma_f32_16x16x32_f16 v[112:115], v[84:87], v[20:23], v[112:115]
	s_cselect_b32 s10, s10, 0
	s_cmp_ge_i32 s45, s40
	s_cselect_b32 s10, s10, 0
	s_or_b32 s12, s11, s10
	ds_read_b128 v[80:83], v65 offset:4096
	ds_read_b128 v[76:79], v65 offset:5120
	ds_read_b128 v[72:75], v65 offset:6144
	ds_read_b128 v[68:71], v65 offset:7168
	s_bitcmp1_b32 s44, 1
	s_cbranch_scc0 .Lat_noga_ya0
	v_add_f32_e32 v100, v100, v222
	v_add_f32_e32 v101, v101, v223
	v_add_f32_e32 v102, v102, v224
	v_add_f32_e32 v103, v103, v225
	v_add_f32_e32 v104, v104, v226
	v_add_f32_e32 v105, v105, v227
	v_add_f32_e32 v106, v106, v228
	v_add_f32_e32 v107, v107, v229
	v_add_f32_e32 v108, v108, v230
	v_add_f32_e32 v109, v109, v231
	v_add_f32_e32 v110, v110, v232
	v_add_f32_e32 v111, v111, v233
	v_add_f32_e32 v112, v112, v234
	v_add_f32_e32 v113, v113, v235
	v_add_f32_e32 v114, v114, v236
	v_add_f32_e32 v115, v115, v237

; #define MFMA16(a, b, c) __builtin_amdgcn_mfma_f32_16x16x32_f16((a), (b), (c), 0, 0, 0)
; #define RING_ISSUE(SI) do { int kbi = kb0 + (SI) * 32; if (kbi > kb_last) kbi = kb_last; const int slot = (SI) % 3; \
;           const h16* srcp = wave < 4 ? kbase + (size_t)kbi * LDH + k_src_off : vT + (size_t)(kbi >> 5) * 2048 + v_src_off; \
;           __builtin_amdgcn_global_load_lds((const unsigned*)srcp, (LAS unsigned*)(ring + slot * 8192 + stage_dst), 16, 0, 0); } while (0)
; template <bool SEL, bool GEN>
; DI void attn_step(const KF& kv, const int kb, const int t, const int lane, const bool selbit,
;                   const LAS float* tabh, const half8 (&q)[2][2], f32x4 (&O)[2][4], const float (&nR)[2], float (&l)[2]) {
;     ...
;       s[hp][kt] = MFMA16(kv.k[kt][0], q[hp][0], c0);
;       s[hp][kt] = MFMA16(kv.k[kt][1], q[hp][1], s[hp][kt]);
;     }
;   }
;   if (GEN) {
;     const int d0 = t - kb - fq * 4;
; #pragma unroll
;     for (int kt = 0; kt < 2; ++kt)
; #pragma unroll
;       for (int j = 0; j < 4; ++j) {
;         const int dist = d0 - (kt * 16 + j);
;         const bool bad = SEL ? (dist < 0) : ((unsigned)dist >= 512u);
;         const int ix = bad ? 130 : (dist > 128 ? 128 : dist);
; #pragma unroll
;         for (int hp = 0; hp < 2; ++hp) s[hp][kt][j] += tabh[hp * 132 + ix];
; DI void attn_phase(const Params& p, const int layer, const int wid_s) {
;     ...
;         for (int si = 0; si < nsteps; ++si) {
;           asm volatile("s_waitcnt vmcnt(1) lgkmcnt(0)" ::: "memory");
;           __builtin_amdgcn_s_barrier();
;           asm volatile("" ::: "memory");
;           RING_ISSUE(si + 2);
;           const int kb = kb0 + si * 32;
;           if (kb > kmax_w || kb < lo_w) continue;
;           if (br == 1 && kb + 31 + 128 <= t0 && __ballot((selmask >> (kb >> 6)) & 1u) == 0ull) continue;
.Lat_yb0:
	s_waitcnt lgkmcnt(0)
	s_and_b32 s44, s12, 2
	s_or_b32 s44, s44, 1
	v_mfma_f32_16x16x32_f16 v[100:103], v[96:99], v[8:11], v[128:131]
	s_add_i32 s8, s45, 64
	s_min_i32 s8, s8, s14
	s_mul_i32 s8, s8, s42
	s_mov_b32 s9, 0
	v_mfma_f32_16x16x32_f16 v[104:107], v[88:91], v[8:11], v[128:131]
	v_lshl_add_u64 v[238:239], v[240:241], 0, s[8:9]
	s_add_i32 m0, s43, s22
	s_nop 0
	global_load_lds_dwordx4 v[238:239], off
	v_mfma_f32_16x16x32_f16 v[108:111], v[96:99], v[16:19], v[132:135]
	s_add_i32 s43, s43, 0x2000
	s_cmp_eq_u32 s43, 0x1f880
	s_cselect_b32 s43, 0x20080, s43
	s_cmp_eq_u32 s43, 0x22080
	s_cselect_b32 s43, 0x19880, s43
	v_mfma_f32_16x16x32_f16 v[112:115], v[88:91], v[16:19], v[132:135]
	s_add_i32 s45, s45, 32
	s_add_i32 s41, s41, -1
	s_add_i32 s10, s45, 0x9f
	s_cmp_gt_i32 s10, s51
	v_mfma_f32_16x16x32_f16 v[100:103], v[92:95], v[12:15], v[100:103]
	s_cselect_b32 s11, 2, 0
	s_add_i32 s10, s45, 0x1f1
	s_cmp_le_i32 s10, s51
	s_cselect_b32 s10, 2, 0
	v_mfma_f32_16x16x32_f16 v[104:107], v[84:87], v[12:15], v[104:107]
	s_and_b32 s10, s10, s4
	s_or_b32 s11, s11, s10
	s_lshr_b32 s10, s45, 6
	v_bfe_u32 v66, v244, s10, 1
	v_cmp_ne_u32_e32 vcc, 0, v66
	v_mfma_f32_16x16x32_f16 v[108:111], v[92:95], v[20:23], v[108:111]
	s_cmp_lg_u64 vcc, 0
	s_cselect_b32 s10, 1, 0
	s_lshr_b32 s9, s11, 1
	s_or_b32 s10, s10, s9
	v_mfma_f32_16x16x32_f16 v[112:115], v[84:87], v[20:23], v[112:115]
	s_cmp_le_i32 s45, s15
	s_cselect_b32 s10, s10, 0
	s_cmp_ge_i32 s45, s40
	s_cselect_b32 s10, s10, 0
	s_or_b32 s12, s11, s10
	ds_read_b128 v[80:83], v65 offset:4096
	ds_read_b128 v[76:79], v65 offset:5120
	ds_read_b128 v[72:75], v65 offset:6144
	ds_read_b128 v[68:71], v65 offset:7168
	s_bitcmp1_b32 s44, 1
	s_cbranch_scc0 .Lat_noga_yb0
	v_add_f32_e32 v100, v100, v222
	v_add_f32_e32 v101, v101, v223
	v_add_f32_e32 v102, v102, v224
	v_add_f32_e32 v103, v103, v225
	v_add_f32_e32 v104, v104, v226
	v_add_f32_e32 v105, v105, v227
	v_add_f32_e32 v106, v106, v228
	v_add_f32_e32 v107, v107, v229
	v_add_f32_e32 v108, v108, v230
	v_add_f32_e32 v109, v109, v231
	v_add_f32_e32 v110, v110, v232
	v_add_f32_e32 v111, v111, v233
	v_add_f32_e32 v112, v112, v234
	v_add_f32_e32 v113, v113, v235
	v_add_f32_e32 v114, v114, v236
	v_add_f32_e32 v115, v115, v237

; #define MFMA16(a, b, c) __builtin_amdgcn_mfma_f32_16x16x32_f16((a), (b), (c), 0, 0, 0)
; template <bool SEL, bool GEN>
; DI void attn_step(const KF& kv, const int kb, const int t, const int lane, const bool selbit,
;                   const LAS float* tabh, const half8 (&q)[2][2], f32x4 (&O)[2][4], const float (&nR)[2], float (&l)[2]) {
;     ...
; #pragma unroll
;   for (int dt = 0; dt < 4; ++dt)
; #pragma unroll
;     for (int hp = 0; hp < 2; ++hp) O[hp][dt] = MFMA16(kv.v[dt], pf[hp], O[hp][dt]);
; DI void attn_phase(const Params& p, const int layer, const int wid_s) {
;     ...
;           if (kb > kmax_w || kb < lo_w) continue;
;           if (br == 1 && kb + 31 + 128 <= t0 && __ballot((selmask >> (kb >> 6)) & 1u) == 0ull) continue;
.Lat_yskip0:
	s_bitcmp1_b32 s44, 0
	s_cbranch_scc0 .Lat_yd0
	s_waitcnt lgkmcnt(0)
	v_mfma_f32_16x16x32_f16 v[60:63], v[80:83], v[120:123], v[60:63]
	v_add_f32_e32 v214, v214, v198
	v_add_f32_e32 v215, v215, v199
	v_add_f32_e32 v216, v216, v200
	v_add_f32_e32 v217, v217, v201
	v_add_f32_e32 v214, v214, v202
	v_add_f32_e32 v215, v215, v203
	v_mfma_f32_16x16x32_f16 v[56:59], v[76:79], v[120:123], v[56:59]
	v_add_f32_e32 v216, v216, v204
	v_add_f32_e32 v217, v217, v205
	v_add_f32_e32 v218, v218, v206
	v_add_f32_e32 v219, v219, v207
	v_add_f32_e32 v220, v220, v208
	v_add_f32_e32 v221, v221, v209
	v_mfma_f32_16x16x32_f16 v[52:55], v[72:75], v[120:123], v[52:55]
	v_add_f32_e32 v218, v218, v210
	v_add_f32_e32 v219, v219, v211
	v_add_f32_e32 v220, v220, v212
	v_add_f32_e32 v221, v221, v213
	s_add_i32 s8, s45, 64
	s_min_i32 s8, s8, s14
	s_mul_i32 s8, s8, s42
	v_mfma_f32_16x16x32_f16 v[48:51], v[68:71], v[120:123], v[48:51]
	s_mov_b32 s9, 0
	v_lshl_add_u64 v[238:239], v[240:241], 0, s[8:9]
	s_add_i32 m0, s43, s22
	s_nop 0
	global_load_lds_dwordx4 v[238:239], off
	s_add_i32 s43, s43, 0x2000
	v_mfma_f32_16x16x32_f16 v[44:47], v[80:83], v[124:127], v[44:47]
	s_cmp_eq_u32 s43, 0x1f880
	s_cselect_b32 s43, 0x20080, s43
	s_cmp_eq_u32 s43, 0x22080
	s_cselect_b32 s43, 0x19880, s43
	s_add_i32 s45, s45, 32
	s_add_i32 s41, s41, -1
	v_mfma_f32_16x16x32_f16 v[40:43], v[76:79], v[124:127], v[40:43]
	s_add_i32 s10, s45, 0x9f
	s_cmp_gt_i32 s10, s51
	s_cselect_b32 s11, 2, 0
	s_add_i32 s10, s45, 0x1f1
	s_cmp_le_i32 s10, s51
	s_cselect_b32 s10, 2, 0
	s_and_b32 s10, s10, s4
	v_mfma_f32_16x16x32_f16 v[36:39], v[72:75], v[124:127], v[36:39]
	s_or_b32 s11, s11, s10
	s_lshr_b32 s10, s45, 6
	v_bfe_u32 v66, v244, s10, 1
	v_cmp_ne_u32_e32 vcc, 0, v66
	s_cmp_lg_u64 vcc, 0
	s_cselect_b32 s10, 1, 0
	v_mfma_f32_16x16x32_f16 v[32:35], v[68:71], v[124:127], v[32:35]
	s_lshr_b32 s9, s11, 1
	s_or_b32 s10, s10, s9
	s_cmp_le_i32 s45, s15
	s_cselect_b32 s10, s10, 0
	s_cmp_ge_i32 s45, s40
	s_cselect_b32 s10, s10, 0
	s_or_b32 s12, s11, s10
	s_mov_b32 s44, 0
	s_cmp_lg_u32 s41, 0
	s_cbranch_scc1 .Lat_ytop1
	s_branch .Lat_yexit

; #define MFMA16(a, b, c) __builtin_amdgcn_mfma_f32_16x16x32_f16((a), (b), (c), 0, 0, 0)
; #define LAS __attribute__((address_space(3)))
; template <bool SEL, bool GEN>
; DI void attn_step(const KF& kv, const int kb, const int t, const int lane, const bool selbit,
;                   const LAS float* tabh, const half8 (&q)[2][2], f32x4 (&O)[2][4], const float (&nR)[2], float (&l)[2]) {
;     ...
;       s[hp][kt] = MFMA16(kv.k[kt][0], q[hp][0], c0);
;       s[hp][kt] = MFMA16(kv.k[kt][1], q[hp][1], s[hp][kt]);
;     }
;   }
;   if (GEN) {
;     const int d0 = t - kb - fq * 4;
; #pragma unroll
;     for (int kt = 0; kt < 2; ++kt)
; #pragma unroll
;       for (int j = 0; j < 4; ++j) {
;         const int dist = d0 - (kt * 16 + j);
;         const bool bad = SEL ? (dist < 0) : ((unsigned)dist >= 512u);
;         const int ix = bad ? 130 : (dist > 128 ? 128 : dist);
; #pragma unroll
;         for (int hp = 0; hp < 2; ++hp) s[hp][kt][j] += tabh[hp * 132 + ix];
;     ...
; #pragma unroll
;   for (int dt = 0; dt < 4; ++dt)
; #pragma unroll
;     for (int hp = 0; hp < 2; ++hp) O[hp][dt] = MFMA16(kv.v[dt], pf[hp], O[hp][dt]);
; DI void attn_phase(const Params& p, const int layer, const int wid_s) {
;     ...
;           LAS unsigned char* slotp = ring + (si % 3) * 8192;
;           KF kv;
; #pragma unroll
;           for (int kt = 0; kt < 2; ++kt)
; #pragma unroll
;             for (int ks = 0; ks < 2; ++ks) kv.k[kt][ks] = *(const LAS half8*)(slotp + kread[kt][ks]);
; #pragma unroll
;           for (int dt = 0; dt < 4; ++dt) kv.v[dt] = *(const LAS half8*)(slotp + vread[dt]);
;           if (br == 1) {
;             const bool bit = (selmask >> (kb >> 6)) & 1u;
;             if (kb + 31 + 128 <= t0) attn_step<true, false>(kv, kb, t, lane, bit, tabh, q, O, nRs, l);
;             else attn_step<true, true>(kv, kb, t, lane, bit, tabh, q, O, nRs, l);
.Lat_nogi_yt1:
	ds_read_b128 v[96:99], v0 offset:8192
	ds_read_b128 v[92:95], v64 offset:8192
	ds_read_b128 v[88:91], v0 offset:10240
	ds_read_b128 v[84:87], v64 offset:10240
	s_lshr_b32 s10, s45, 6
	s_cmp_eq_u32 s10, s13
	s_cbranch_scc1 .Lat_cok_y1
	s_mov_b32 s13, s10
	v_bfe_u32 v66, v244, s10, 1
	v_cmp_ne_u32_e32 vcc, 0, v66
	s_nop 1
	v_cndmask_b32_e32 v128, v4, v242, vcc
	v_cndmask_b32_e32 v132, v4, v243, vcc
	v_cndmask_b32_e32 v129, v4, v242, vcc
	v_cndmask_b32_e32 v133, v4, v243, vcc
	v_cndmask_b32_e32 v130, v4, v242, vcc
	v_cndmask_b32_e32 v134, v4, v243, vcc
	v_cndmask_b32_e32 v131, v4, v242, vcc
	v_cndmask_b32_e32 v135, v4, v243, vcc
.Lat_cok_y1:
	s_bitcmp1_b32 s44, 0
	s_cbranch_scc0 .Lat_yb1
	s_waitcnt lgkmcnt(4)
	v_mfma_f32_16x16x32_f16 v[60:63], v[80:83], v[120:123], v[60:63]
	v_add_f32_e32 v214, v214, v198
	v_add_f32_e32 v215, v215, v199
	v_add_f32_e32 v216, v216, v200
	v_mfma_f32_16x16x32_f16 v[56:59], v[76:79], v[120:123], v[56:59]
	v_add_f32_e32 v217, v217, v201
	v_add_f32_e32 v214, v214, v202
	v_add_f32_e32 v215, v215, v203
	v_mfma_f32_16x16x32_f16 v[52:55], v[72:75], v[120:123], v[52:55]
	v_add_f32_e32 v216, v216, v204
	v_add_f32_e32 v217, v217, v205
	v_add_f32_e32 v218, v218, v206
	v_mfma_f32_16x16x32_f16 v[48:51], v[68:71], v[120:123], v[48:51]
	v_add_f32_e32 v219, v219, v207
	v_add_f32_e32 v220, v220, v208
	v_add_f32_e32 v221, v221, v209
	v_mfma_f32_16x16x32_f16 v[44:47], v[80:83], v[124:127], v[44:47]
	v_add_f32_e32 v218, v218, v210
	v_add_f32_e32 v219, v219, v211
	v_add_f32_e32 v220, v220, v212
	v_mfma_f32_16x16x32_f16 v[40:43], v[76:79], v[124:127], v[40:43]
	v_add_f32_e32 v221, v221, v213
	s_add_i32 s8, s45, 64
	s_min_i32 s8, s8, s14
	v_mfma_f32_16x16x32_f16 v[36:39], v[72:75], v[124:127], v[36:39]
	s_mul_i32 s8, s8, s42
	s_mov_b32 s9, 0
	v_lshl_add_u64 v[238:239], v[240:241], 0, s[8:9]
	v_mfma_f32_16x16x32_f16 v[32:35], v[68:71], v[124:127], v[32:35]
	s_add_i32 m0, s43, s22
	s_nop 0
	global_load_lds_dwordx4 v[238:239], off
	s_waitcnt lgkmcnt(0)
	s_and_b32 s44, s12, 2
	s_or_b32 s44, s44, 1
	v_mfma_f32_16x16x32_f16 v[100:103], v[96:99], v[8:11], v[128:131]
	s_add_i32 s43, s43, 0x2000
	s_cmp_eq_u32 s43, 0x1f880
	s_cselect_b32 s43, 0x20080, s43
	v_mfma_f32_16x16x32_f16 v[104:107], v[88:91], v[8:11], v[128:131]
	s_cmp_eq_u32 s43, 0x22080
	s_cselect_b32 s43, 0x19880, s43
	s_add_i32 s45, s45, 32
	v_mfma_f32_16x16x32_f16 v[108:111], v[96:99], v[16:19], v[132:135]
	s_add_i32 s41, s41, -1
	s_add_i32 s10, s45, 0x9f
	s_cmp_gt_i32 s10, s51
	s_cselect_b32 s11, 2, 0
	v_mfma_f32_16x16x32_f16 v[112:115], v[88:91], v[16:19], v[132:135]
	s_add_i32 s10, s45, 0x1f1
	s_cmp_le_i32 s10, s51
	s_cselect_b32 s10, 2, 0
	v_mfma_f32_16x16x32_f16 v[100:103], v[92:95], v[12:15], v[100:103]
	s_and_b32 s10, s10, s4
	s_or_b32 s11, s11, s10
	s_lshr_b32 s10, s45, 6
	v_mfma_f32_16x16x32_f16 v[104:107], v[84:87], v[12:15], v[104:107]
	v_bfe_u32 v66, v244, s10, 1
	v_cmp_ne_u32_e32 vcc, 0, v66
	s_cmp_lg_u64 vcc, 0
	s_cselect_b32 s10, 1, 0
	v_mfma_f32_16x16x32_f16 v[108:111], v[92:95], v[20:23], v[108:111]
	s_lshr_b32 s9, s11, 1
	s_or_b32 s10, s10, s9
	s_cmp_le_i32 s45, s15
	v_mfma_f32_16x16x32_f16 v[112:115], v[84:87], v[20:23], v[112:115]
	s_cselect_b32 s10, s10, 0
	s_cmp_ge_i32 s45, s40
	s_cselect_b32 s10, s10, 0
	s_or_b32 s12, s11, s10
	ds_read_b128 v[80:83], v65 offset:12288
	ds_read_b128 v[76:79], v65 offset:13312
	ds_read_b128 v[72:75], v65 offset:14336
	ds_read_b128 v[68:71], v65 offset:15360
	s_bitcmp1_b32 s44, 1
	s_cbranch_scc0 .Lat_noga_ya1
	v_add_f32_e32 v100, v100, v222
	v_add_f32_e32 v101, v101, v223
	v_add_f32_e32 v102, v102, v224
	v_add_f32_e32 v103, v103, v225
	v_add_f32_e32 v104, v104, v226
	v_add_f32_e32 v105, v105, v227
	v_add_f32_e32 v106, v106, v228
	v_add_f32_e32 v107, v107, v229
	v_add_f32_e32 v108, v108, v230
	v_add_f32_e32 v109, v109, v231
	v_add_f32_e32 v110, v110, v232
	v_add_f32_e32 v111, v111, v233
	v_add_f32_e32 v112, v112, v234
	v_add_f32_e32 v113, v113, v235
	v_add_f32_e32 v114, v114, v236
	v_add_f32_e32 v115, v115, v237

; #define MFMA16(a, b, c) __builtin_amdgcn_mfma_f32_16x16x32_f16((a), (b), (c), 0, 0, 0)
; #define RING_ISSUE(SI) do { int kbi = kb0 + (SI) * 32; if (kbi > kb_last) kbi = kb_last; const int slot = (SI) % 3; \
;           const h16* srcp = wave < 4 ? kbase + (size_t)kbi * LDH + k_src_off : vT + (size_t)(kbi >> 5) * 2048 + v_src_off; \
;           __builtin_amdgcn_global_load_lds((const unsigned*)srcp, (LAS unsigned*)(ring + slot * 8192 + stage_dst), 16, 0, 0); } while (0)
; template <bool SEL, bool GEN>
; DI void attn_step(const KF& kv, const int kb, const int t, const int lane, const bool selbit,
;                   const LAS float* tabh, const half8 (&q)[2][2], f32x4 (&O)[2][4], const float (&nR)[2], float (&l)[2]) {
;     ...
;       s[hp][kt] = MFMA16(kv.k[kt][0], q[hp][0], c0);
;       s[hp][kt] = MFMA16(kv.k[kt][1], q[hp][1], s[hp][kt]);
;     }
;   }
;   if (GEN) {
;     const int d0 = t - kb - fq * 4;
; #pragma unroll
;     for (int kt = 0; kt < 2; ++kt)
; #pragma unroll
;       for (int j = 0; j < 4; ++j) {
;         const int dist = d0 - (kt * 16 + j);
;         const bool bad = SEL ? (dist < 0) : ((unsigned)dist >= 512u);
;         const int ix = bad ? 130 : (dist > 128 ? 128 : dist);
; #pragma unroll
;         for (int hp = 0; hp < 2; ++hp) s[hp][kt][j] += tabh[hp * 132 + ix];
; DI void attn_phase(const Params& p, const int layer, const int wid_s) {
;     ...
;         for (int si = 0; si < nsteps; ++si) {
;           asm volatile("s_waitcnt vmcnt(1) lgkmcnt(0)" ::: "memory");
;           __builtin_amdgcn_s_barrier();
;           asm volatile("" ::: "memory");
;           RING_ISSUE(si + 2);
;           const int kb = kb0 + si * 32;
;           if (kb > kmax_w || kb < lo_w) continue;
;           if (br == 1 && kb + 31 + 128 <= t0 && __ballot((selmask >> (kb >> 6)) & 1u) == 0ull) continue;
.Lat_yb1:
	s_waitcnt lgkmcnt(0)
	s_and_b32 s44, s12, 2
	s_or_b32 s44, s44, 1
	v_mfma_f32_16x16x32_f16 v[100:103], v[96:99], v[8:11], v[128:131]
	s_add_i32 s8, s45, 64
	s_min_i32 s8, s8, s14
	s_mul_i32 s8, s8, s42
	s_mov_b32 s9, 0
	v_mfma_f32_16x16x32_f16 v[104:107], v[88:91], v[8:11], v[128:131]
	v_lshl_add_u64 v[238:239], v[240:241], 0, s[8:9]
	s_add_i32 m0, s43, s22
	s_nop 0
	global_load_lds_dwordx4 v[238:239], off
	v_mfma_f32_16x16x32_f16 v[108:111], v[96:99], v[16:19], v[132:135]
	s_add_i32 s43, s43, 0x2000
	s_cmp_eq_u32 s43, 0x1f880
	s_cselect_b32 s43, 0x20080, s43
	s_cmp_eq_u32 s43, 0x22080
	s_cselect_b32 s43, 0x19880, s43
	v_mfma_f32_16x16x32_f16 v[112:115], v[88:91], v[16:19], v[132:135]
	s_add_i32 s45, s45, 32
	s_add_i32 s41, s41, -1
	s_add_i32 s10, s45, 0x9f
	s_cmp_gt_i32 s10, s51
	v_mfma_f32_16x16x32_f16 v[100:103], v[92:95], v[12:15], v[100:103]
	s_cselect_b32 s11, 2, 0
	s_add_i32 s10, s45, 0x1f1
	s_cmp_le_i32 s10, s51
	s_cselect_b32 s10, 2, 0
	v_mfma_f32_16x16x32_f16 v[104:107], v[84:87], v[12:15], v[104:107]
	s_and_b32 s10, s10, s4
	s_or_b32 s11, s11, s10
	s_lshr_b32 s10, s45, 6
	v_bfe_u32 v66, v244, s10, 1
	v_cmp_ne_u32_e32 vcc, 0, v66
	v_mfma_f32_16x16x32_f16 v[108:111], v[92:95], v[20:23], v[108:111]
	s_cmp_lg_u64 vcc, 0
	s_cselect_b32 s10, 1, 0
	s_lshr_b32 s9, s11, 1
	s_or_b32 s10, s10, s9
	v_mfma_f32_16x16x32_f16 v[112:115], v[84:87], v[20:23], v[112:115]
	s_cmp_le_i32 s45, s15
	s_cselect_b32 s10, s10, 0
	s_cmp_ge_i32 s45, s40
	s_cselect_b32 s10, s10, 0
	s_or_b32 s12, s11, s10
	ds_read_b128 v[80:83], v65 offset:12288
	ds_read_b128 v[76:79], v65 offset:13312
	ds_read_b128 v[72:75], v65 offset:14336
	ds_read_b128 v[68:71], v65 offset:15360
	s_bitcmp1_b32 s44, 1
	s_cbranch_scc0 .Lat_noga_yb1
	v_add_f32_e32 v100, v100, v222
	v_add_f32_e32 v101, v101, v223
	v_add_f32_e32 v102, v102, v224
	v_add_f32_e32 v103, v103, v225
	v_add_f32_e32 v104, v104, v226
	v_add_f32_e32 v105, v105, v227
	v_add_f32_e32 v106, v106, v228
	v_add_f32_e32 v107, v107, v229
	v_add_f32_e32 v108, v108, v230
	v_add_f32_e32 v109, v109, v231
	v_add_f32_e32 v110, v110, v232
	v_add_f32_e32 v111, v111, v233
	v_add_f32_e32 v112, v112, v234
	v_add_f32_e32 v113, v113, v235
	v_add_f32_e32 v114, v114, v236
	v_add_f32_e32 v115, v115, v237

; #define MFMA16(a, b, c) __builtin_amdgcn_mfma_f32_16x16x32_f16((a), (b), (c), 0, 0, 0)
; #define LAS __attribute__((address_space(3)))
; template <bool SEL, bool GEN>
; DI void attn_step(const KF& kv, const int kb, const int t, const int lane, const bool selbit,
;                   const LAS float* tabh, const half8 (&q)[2][2], f32x4 (&O)[2][4], const float (&nR)[2], float (&l)[2]) {
;     ...
;       s[hp][kt] = MFMA16(kv.k[kt][0], q[hp][0], c0);
;       s[hp][kt] = MFMA16(kv.k[kt][1], q[hp][1], s[hp][kt]);
;     }
;   }
;   if (GEN) {
;     const int d0 = t - kb - fq * 4;
; #pragma unroll
;     for (int kt = 0; kt < 2; ++kt)
; #pragma unroll
;       for (int j = 0; j < 4; ++j) {
;         const int dist = d0 - (kt * 16 + j);
;         const bool bad = SEL ? (dist < 0) : ((unsigned)dist >= 512u);
;         const int ix = bad ? 130 : (dist > 128 ? 128 : dist);
; #pragma unroll
;         for (int hp = 0; hp < 2; ++hp) s[hp][kt][j] += tabh[hp * 132 + ix];
;     ...
; #pragma unroll
;   for (int dt = 0; dt < 4; ++dt)
; #pragma unroll
;     for (int hp = 0; hp < 2; ++hp) O[hp][dt] = MFMA16(kv.v[dt], pf[hp], O[hp][dt]);
; DI void attn_phase(const Params& p, const int layer, const int wid_s) {
;     ...
;           LAS unsigned char* slotp = ring + (si % 3) * 8192;
;           KF kv;
; #pragma unroll
;           for (int kt = 0; kt < 2; ++kt)
; #pragma unroll
;             for (int ks = 0; ks < 2; ++ks) kv.k[kt][ks] = *(const LAS half8*)(slotp + kread[kt][ks]);
; #pragma unroll
;           for (int dt = 0; dt < 4; ++dt) kv.v[dt] = *(const LAS half8*)(slotp + vread[dt]);
;           if (br == 1) {
;             const bool bit = (selmask >> (kb >> 6)) & 1u;
;             if (kb + 31 + 128 <= t0) attn_step<true, false>(kv, kb, t, lane, bit, tabh, q, O, nRs, l);
;             else attn_step<true, true>(kv, kb, t, lane, bit, tabh, q, O, nRs, l);
.Lat_nogi_yt2:
	ds_read_b128 v[96:99], v0 offset:16384
	ds_read_b128 v[92:95], v64 offset:16384
	ds_read_b128 v[88:91], v0 offset:18432
	ds_read_b128 v[84:87], v64 offset:18432
	s_lshr_b32 s10, s45, 6
	s_cmp_eq_u32 s10, s13
	s_cbranch_scc1 .Lat_cok_y2
	s_mov_b32 s13, s10
	v_bfe_u32 v66, v244, s10, 1
	v_cmp_ne_u32_e32 vcc, 0, v66
	s_nop 1
	v_cndmask_b32_e32 v128, v4, v242, vcc
	v_cndmask_b32_e32 v132, v4, v243, vcc
	v_cndmask_b32_e32 v129, v4, v242, vcc
	v_cndmask_b32_e32 v133, v4, v243, vcc
	v_cndmask_b32_e32 v130, v4, v242, vcc
	v_cndmask_b32_e32 v134, v4, v243, vcc
	v_cndmask_b32_e32 v131, v4, v242, vcc
	v_cndmask_b32_e32 v135, v4, v243, vcc
.Lat_cok_y2:
	s_bitcmp1_b32 s44, 0
	s_cbranch_scc0 .Lat_yb2
	s_waitcnt lgkmcnt(4)
	v_mfma_f32_16x16x32_f16 v[60:63], v[80:83], v[120:123], v[60:63]
	v_add_f32_e32 v214, v214, v198
	v_add_f32_e32 v215, v215, v199
	v_add_f32_e32 v216, v216, v200
	v_mfma_f32_16x16x32_f16 v[56:59], v[76:79], v[120:123], v[56:59]
	v_add_f32_e32 v217, v217, v201
	v_add_f32_e32 v214, v214, v202
	v_add_f32_e32 v215, v215, v203
	v_mfma_f32_16x16x32_f16 v[52:55], v[72:75], v[120:123], v[52:55]
	v_add_f32_e32 v216, v216, v204
	v_add_f32_e32 v217, v217, v205
	v_add_f32_e32 v218, v218, v206
	v_mfma_f32_16x16x32_f16 v[48:51], v[68:71], v[120:123], v[48:51]
	v_add_f32_e32 v219, v219, v207
	v_add_f32_e32 v220, v220, v208
	v_add_f32_e32 v221, v221, v209
	v_mfma_f32_16x16x32_f16 v[44:47], v[80:83], v[124:127], v[44:47]
	v_add_f32_e32 v218, v218, v210
	v_add_f32_e32 v219, v219, v211
	v_add_f32_e32 v220, v220, v212
	v_mfma_f32_16x16x32_f16 v[40:43], v[76:79], v[124:127], v[40:43]
	v_add_f32_e32 v221, v221, v213
	s_add_i32 s8, s45, 64
	s_min_i32 s8, s8, s14
	v_mfma_f32_16x16x32_f16 v[36:39], v[72:75], v[124:127], v[36:39]
	s_mul_i32 s8, s8, s42
	s_mov_b32 s9, 0
	v_lshl_add_u64 v[238:239], v[240:241], 0, s[8:9]
	v_mfma_f32_16x16x32_f16 v[32:35], v[68:71], v[124:127], v[32:35]
	s_add_i32 m0, s43, s22
	s_nop 0
	global_load_lds_dwordx4 v[238:239], off
	s_waitcnt lgkmcnt(0)
	s_and_b32 s44, s12, 2
	s_or_b32 s44, s44, 1
	v_mfma_f32_16x16x32_f16 v[100:103], v[96:99], v[8:11], v[128:131]
	s_add_i32 s43, s43, 0x2000
	s_cmp_eq_u32 s43, 0x1f880
	s_cselect_b32 s43, 0x20080, s43
	v_mfma_f32_16x16x32_f16 v[104:107], v[88:91], v[8:11], v[128:131]
	s_cmp_eq_u32 s43, 0x22080
	s_cselect_b32 s43, 0x19880, s43
	s_add_i32 s45, s45, 32
	v_mfma_f32_16x16x32_f16 v[108:111], v[96:99], v[16:19], v[132:135]
	s_add_i32 s41, s41, -1
	s_add_i32 s10, s45, 0x9f
	s_cmp_gt_i32 s10, s51
	s_cselect_b32 s11, 2, 0
	v_mfma_f32_16x16x32_f16 v[112:115], v[88:91], v[16:19], v[132:135]
	s_add_i32 s10, s45, 0x1f1
	s_cmp_le_i32 s10, s51
	s_cselect_b32 s10, 2, 0
	v_mfma_f32_16x16x32_f16 v[100:103], v[92:95], v[12:15], v[100:103]
	s_and_b32 s10, s10, s4
	s_or_b32 s11, s11, s10
	s_lshr_b32 s10, s45, 6
	v_mfma_f32_16x16x32_f16 v[104:107], v[84:87], v[12:15], v[104:107]
	v_bfe_u32 v66, v244, s10, 1
	v_cmp_ne_u32_e32 vcc, 0, v66
	s_cmp_lg_u64 vcc, 0
	s_cselect_b32 s10, 1, 0
	v_mfma_f32_16x16x32_f16 v[108:111], v[92:95], v[20:23], v[108:111]
	s_lshr_b32 s9, s11, 1
	s_or_b32 s10, s10, s9
	s_cmp_le_i32 s45, s15
	v_mfma_f32_16x16x32_f16 v[112:115], v[84:87], v[20:23], v[112:115]
	s_cselect_b32 s10, s10, 0
	s_cmp_ge_i32 s45, s40
	s_cselect_b32 s10, s10, 0
	s_or_b32 s12, s11, s10
	ds_read_b128 v[80:83], v65 offset:20480
	ds_read_b128 v[76:79], v65 offset:21504
	ds_read_b128 v[72:75], v65 offset:22528
	ds_read_b128 v[68:71], v65 offset:23552
	s_bitcmp1_b32 s44, 1
	s_cbranch_scc0 .Lat_noga_ya2
	v_add_f32_e32 v100, v100, v222
	v_add_f32_e32 v101, v101, v223
	v_add_f32_e32 v102, v102, v224
	v_add_f32_e32 v103, v103, v225
	v_add_f32_e32 v104, v104, v226
	v_add_f32_e32 v105, v105, v227
	v_add_f32_e32 v106, v106, v228
	v_add_f32_e32 v107, v107, v229
	v_add_f32_e32 v108, v108, v230
	v_add_f32_e32 v109, v109, v231
	v_add_f32_e32 v110, v110, v232
	v_add_f32_e32 v111, v111, v233
	v_add_f32_e32 v112, v112, v234
	v_add_f32_e32 v113, v113, v235
	v_add_f32_e32 v114, v114, v236
	v_add_f32_e32 v115, v115, v237

; #define MFMA16(a, b, c) __builtin_amdgcn_mfma_f32_16x16x32_f16((a), (b), (c), 0, 0, 0)
; #define RING_ISSUE(SI) do { int kbi = kb0 + (SI) * 32; if (kbi > kb_last) kbi = kb_last; const int slot = (SI) % 3; \
;           const h16* srcp = wave < 4 ? kbase + (size_t)kbi * LDH + k_src_off : vT + (size_t)(kbi >> 5) * 2048 + v_src_off; \
;           __builtin_amdgcn_global_load_lds((const unsigned*)srcp, (LAS unsigned*)(ring + slot * 8192 + stage_dst), 16, 0, 0); } while (0)
; template <bool SEL, bool GEN>
; DI void attn_step(const KF& kv, const int kb, const int t, const int lane, const bool selbit,
;                   const LAS float* tabh, const half8 (&q)[2][2], f32x4 (&O)[2][4], const float (&nR)[2], float (&l)[2]) {
;     ...
;       s[hp][kt] = MFMA16(kv.k[kt][0], q[hp][0], c0);
;       s[hp][kt] = MFMA16(kv.k[kt][1], q[hp][1], s[hp][kt]);
;     }
;   }
;   if (GEN) {
;     const int d0 = t - kb - fq * 4;
; #pragma unroll
;     for (int kt = 0; kt < 2; ++kt)
; #pragma unroll
;       for (int j = 0; j < 4; ++j) {
;         const int dist = d0 - (kt * 16 + j);
;         const bool bad = SEL ? (dist < 0) : ((unsigned)dist >= 512u);
;         const int ix = bad ? 130 : (dist > 128 ? 128 : dist);
; #pragma unroll
;         for (int hp = 0; hp < 2; ++hp) s[hp][kt][j] += tabh[hp * 132 + ix];
; DI void attn_phase(const Params& p, const int layer, const int wid_s) {
;     ...
;         for (int si = 0; si < nsteps; ++si) {
;           asm volatile("s_waitcnt vmcnt(1) lgkmcnt(0)" ::: "memory");
;           __builtin_amdgcn_s_barrier();
;           asm volatile("" ::: "memory");
;           RING_ISSUE(si + 2);
;           const int kb = kb0 + si * 32;
;           if (kb > kmax_w || kb < lo_w) continue;
;           if (br == 1 && kb + 31 + 128 <= t0 && __ballot((selmask >> (kb >> 6)) & 1u) == 0ull) continue;
.Lat_yb2:
	s_waitcnt lgkmcnt(0)
	s_and_b32 s44, s12, 2
	s_or_b32 s44, s44, 1
	v_mfma_f32_16x16x32_f16 v[100:103], v[96:99], v[8:11], v[128:131]
	s_add_i32 s8, s45, 64
	s_min_i32 s8, s8, s14
	s_mul_i32 s8, s8, s42
	s_mov_b32 s9, 0
	v_mfma_f32_16x16x32_f16 v[104:107], v[88:91], v[8:11], v[128:131]
	v_lshl_add_u64 v[238:239], v[240:241], 0, s[8:9]
	s_add_i32 m0, s43, s22
	s_nop 0
	global_load_lds_dwordx4 v[238:239], off
	v_mfma_f32_16x16x32_f16 v[108:111], v[96:99], v[16:19], v[132:135]
	s_add_i32 s43, s43, 0x2000
	s_cmp_eq_u32 s43, 0x1f880
	s_cselect_b32 s43, 0x20080, s43
	s_cmp_eq_u32 s43, 0x22080
	s_cselect_b32 s43, 0x19880, s43
	v_mfma_f32_16x16x32_f16 v[112:115], v[88:91], v[16:19], v[132:135]
	s_add_i32 s45, s45, 32
	s_add_i32 s41, s41, -1
	s_add_i32 s10, s45, 0x9f
	s_cmp_gt_i32 s10, s51
	v_mfma_f32_16x16x32_f16 v[100:103], v[92:95], v[12:15], v[100:103]
	s_cselect_b32 s11, 2, 0
	s_add_i32 s10, s45, 0x1f1
	s_cmp_le_i32 s10, s51
	s_cselect_b32 s10, 2, 0
	v_mfma_f32_16x16x32_f16 v[104:107], v[84:87], v[12:15], v[104:107]
	s_and_b32 s10, s10, s4
	s_or_b32 s11, s11, s10
	s_lshr_b32 s10, s45, 6
	v_bfe_u32 v66, v244, s10, 1
	v_cmp_ne_u32_e32 vcc, 0, v66
	v_mfma_f32_16x16x32_f16 v[108:111], v[92:95], v[20:23], v[108:111]
	s_cmp_lg_u64 vcc, 0
	s_cselect_b32 s10, 1, 0
	s_lshr_b32 s9, s11, 1
	s_or_b32 s10, s10, s9
	v_mfma_f32_16x16x32_f16 v[112:115], v[84:87], v[20:23], v[112:115]
	s_cmp_le_i32 s45, s15
	s_cselect_b32 s10, s10, 0
	s_cmp_ge_i32 s45, s40
	s_cselect_b32 s10, s10, 0
	s_or_b32 s12, s11, s10
	ds_read_b128 v[80:83], v65 offset:20480
	ds_read_b128 v[76:79], v65 offset:21504
	ds_read_b128 v[72:75], v65 offset:22528
	ds_read_b128 v[68:71], v65 offset:23552
	s_bitcmp1_b32 s44, 1
	s_cbranch_scc0 .Lat_noga_yb2
	v_add_f32_e32 v100, v100, v222
	v_add_f32_e32 v101, v101, v223
	v_add_f32_e32 v102, v102, v224
	v_add_f32_e32 v103, v103, v225
	v_add_f32_e32 v104, v104, v226
	v_add_f32_e32 v105, v105, v227
	v_add_f32_e32 v106, v106, v228
	v_add_f32_e32 v107, v107, v229
	v_add_f32_e32 v108, v108, v230
	v_add_f32_e32 v109, v109, v231
	v_add_f32_e32 v110, v110, v232
	v_add_f32_e32 v111, v111, v233
	v_add_f32_e32 v112, v112, v234
	v_add_f32_e32 v113, v113, v235
	v_add_f32_e32 v114, v114, v236
	v_add_f32_e32 v115, v115, v237

; #define MFMA16(a, b, c) __builtin_amdgcn_mfma_f32_16x16x32_f16((a), (b), (c), 0, 0, 0)
; #define LAS __attribute__((address_space(3)))
; template <bool SEL, bool GEN>
; DI void attn_step(const KF& kv, const int kb, const int t, const int lane, const bool selbit,
;                   const LAS float* tabh, const half8 (&q)[2][2], f32x4 (&O)[2][4], const float (&nR)[2], float (&l)[2]) {
;     ...
;       s[hp][kt] = MFMA16(kv.k[kt][0], q[hp][0], c0);
;       s[hp][kt] = MFMA16(kv.k[kt][1], q[hp][1], s[hp][kt]);
;     }
;   }
;   if (GEN) {
;     const int d0 = t - kb - fq * 4;
; #pragma unroll
;     for (int kt = 0; kt < 2; ++kt)
; #pragma unroll
;       for (int j = 0; j < 4; ++j) {
;         const int dist = d0 - (kt * 16 + j);
;         const bool bad = SEL ? (dist < 0) : ((unsigned)dist >= 512u);
;         const int ix = bad ? 130 : (dist > 128 ? 128 : dist);
; #pragma unroll
;         for (int hp = 0; hp < 2; ++hp) s[hp][kt][j] += tabh[hp * 132 + ix];
;     ...
; #pragma unroll
;   for (int dt = 0; dt < 4; ++dt)
; #pragma unroll
;     for (int hp = 0; hp < 2; ++hp) O[hp][dt] = MFMA16(kv.v[dt], pf[hp], O[hp][dt]);
; DI void attn_phase(const Params& p, const int layer, const int wid_s) {
;     ...
;           LAS unsigned char* slotp = ring + (si % 3) * 8192;
;           KF kv;
; #pragma unroll
;           for (int kt = 0; kt < 2; ++kt)
; #pragma unroll
;             for (int ks = 0; ks < 2; ++ks) kv.k[kt][ks] = *(const LAS half8*)(slotp + kread[kt][ks]);
; #pragma unroll
;           for (int dt = 0; dt < 4; ++dt) kv.v[dt] = *(const LAS half8*)(slotp + vread[dt]);
;           if (br == 1) {
;             const bool bit = (selmask >> (kb >> 6)) & 1u;
;             if (kb + 31 + 128 <= t0) attn_step<true, false>(kv, kb, t, lane, bit, tabh, q, O, nRs, l);
;             else attn_step<true, true>(kv, kb, t, lane, bit, tabh, q, O, nRs, l);
.Lat_nogi_yt3:
	ds_read_b128 v[96:99], v0 offset:26624
	ds_read_b128 v[92:95], v64 offset:26624
	ds_read_b128 v[88:91], v0 offset:28672
	ds_read_b128 v[84:87], v64 offset:28672
	s_lshr_b32 s10, s45, 6
	s_cmp_eq_u32 s10, s13
	s_cbranch_scc1 .Lat_cok_y3
	s_mov_b32 s13, s10
	v_bfe_u32 v66, v244, s10, 1
	v_cmp_ne_u32_e32 vcc, 0, v66
	s_nop 1
	v_cndmask_b32_e32 v128, v4, v242, vcc
	v_cndmask_b32_e32 v132, v4, v243, vcc
	v_cndmask_b32_e32 v129, v4, v242, vcc
	v_cndmask_b32_e32 v133, v4, v243, vcc
	v_cndmask_b32_e32 v130, v4, v242, vcc
	v_cndmask_b32_e32 v134, v4, v243, vcc
	v_cndmask_b32_e32 v131, v4, v242, vcc
	v_cndmask_b32_e32 v135, v4, v243, vcc
.Lat_cok_y3:
	s_bitcmp1_b32 s44, 0
	s_cbranch_scc0 .Lat_yb3
	s_waitcnt lgkmcnt(4)
	v_mfma_f32_16x16x32_f16 v[60:63], v[80:83], v[120:123], v[60:63]
	v_add_f32_e32 v214, v214, v198
	v_add_f32_e32 v215, v215, v199
	v_add_f32_e32 v216, v216, v200
	v_mfma_f32_16x16x32_f16 v[56:59], v[76:79], v[120:123], v[56:59]
	v_add_f32_e32 v217, v217, v201
	v_add_f32_e32 v214, v214, v202
	v_add_f32_e32 v215, v215, v203
	v_mfma_f32_16x16x32_f16 v[52:55], v[72:75], v[120:123], v[52:55]
	v_add_f32_e32 v216, v216, v204
	v_add_f32_e32 v217, v217, v205
	v_add_f32_e32 v218, v218, v206
	v_mfma_f32_16x16x32_f16 v[48:51], v[68:71], v[120:123], v[48:51]
	v_add_f32_e32 v219, v219, v207
	v_add_f32_e32 v220, v220, v208
	v_add_f32_e32 v221, v221, v209
	v_mfma_f32_16x16x32_f16 v[44:47], v[80:83], v[124:127], v[44:47]
	v_add_f32_e32 v218, v218, v210
	v_add_f32_e32 v219, v219, v211
	v_add_f32_e32 v220, v220, v212
	v_mfma_f32_16x16x32_f16 v[40:43], v[76:79], v[124:127], v[40:43]
	v_add_f32_e32 v221, v221, v213
	s_add_i32 s8, s45, 64
	s_min_i32 s8, s8, s14
	v_mfma_f32_16x16x32_f16 v[36:39], v[72:75], v[124:127], v[36:39]
	s_mul_i32 s8, s8, s42
	s_mov_b32 s9, 0
	v_lshl_add_u64 v[238:239], v[240:241], 0, s[8:9]
	v_mfma_f32_16x16x32_f16 v[32:35], v[68:71], v[124:127], v[32:35]
	s_add_i32 m0, s43, s22
	s_nop 0
	global_load_lds_dwordx4 v[238:239], off
	s_waitcnt lgkmcnt(0)
	s_and_b32 s44, s12, 2
	s_or_b32 s44, s44, 1
	v_mfma_f32_16x16x32_f16 v[100:103], v[96:99], v[8:11], v[128:131]
	s_add_i32 s43, s43, 0x2000
	s_cmp_eq_u32 s43, 0x1f880
	s_cselect_b32 s43, 0x20080, s43
	v_mfma_f32_16x16x32_f16 v[104:107], v[88:91], v[8:11], v[128:131]
	s_cmp_eq_u32 s43, 0x22080
	s_cselect_b32 s43, 0x19880, s43
	s_add_i32 s45, s45, 32
	v_mfma_f32_16x16x32_f16 v[108:111], v[96:99], v[16:19], v[132:135]
	s_add_i32 s41, s41, -1
	s_add_i32 s10, s45, 0x9f
	s_cmp_gt_i32 s10, s51
	s_cselect_b32 s11, 2, 0
	v_mfma_f32_16x16x32_f16 v[112:115], v[88:91], v[16:19], v[132:135]
	s_add_i32 s10, s45, 0x1f1
	s_cmp_le_i32 s10, s51
	s_cselect_b32 s10, 2, 0
	v_mfma_f32_16x16x32_f16 v[100:103], v[92:95], v[12:15], v[100:103]
	s_and_b32 s10, s10, s4
	s_or_b32 s11, s11, s10
	s_lshr_b32 s10, s45, 6
	v_mfma_f32_16x16x32_f16 v[104:107], v[84:87], v[12:15], v[104:107]
	v_bfe_u32 v66, v244, s10, 1
	v_cmp_ne_u32_e32 vcc, 0, v66
	s_cmp_lg_u64 vcc, 0
	s_cselect_b32 s10, 1, 0
	v_mfma_f32_16x16x32_f16 v[108:111], v[92:95], v[20:23], v[108:111]
	s_lshr_b32 s9, s11, 1
	s_or_b32 s10, s10, s9
	s_cmp_le_i32 s45, s15
	v_mfma_f32_16x16x32_f16 v[112:115], v[84:87], v[20:23], v[112:115]
	s_cselect_b32 s10, s10, 0
	s_cmp_ge_i32 s45, s40
	s_cselect_b32 s10, s10, 0
	s_or_b32 s12, s11, s10
	ds_read_b128 v[80:83], v65 offset:30720
	ds_read_b128 v[76:79], v65 offset:31744
	ds_read_b128 v[72:75], v65 offset:32768
	ds_read_b128 v[68:71], v65 offset:33792
	s_bitcmp1_b32 s44, 1
	s_cbranch_scc0 .Lat_noga_ya3
	v_add_f32_e32 v100, v100, v222
	v_add_f32_e32 v101, v101, v223
	v_add_f32_e32 v102, v102, v224
	v_add_f32_e32 v103, v103, v225
	v_add_f32_e32 v104, v104, v226
	v_add_f32_e32 v105, v105, v227
	v_add_f32_e32 v106, v106, v228
	v_add_f32_e32 v107, v107, v229
	v_add_f32_e32 v108, v108, v230
	v_add_f32_e32 v109, v109, v231
	v_add_f32_e32 v110, v110, v232
	v_add_f32_e32 v111, v111, v233
	v_add_f32_e32 v112, v112, v234
	v_add_f32_e32 v113, v113, v235
	v_add_f32_e32 v114, v114, v236
	v_add_f32_e32 v115, v115, v237

; #define MFMA16(a, b, c) __builtin_amdgcn_mfma_f32_16x16x32_f16((a), (b), (c), 0, 0, 0)
; #define RING_ISSUE(SI) do { int kbi = kb0 + (SI) * 32; if (kbi > kb_last) kbi = kb_last; const int slot = (SI) % 3; \
;           const h16* srcp = wave < 4 ? kbase + (size_t)kbi * LDH + k_src_off : vT + (size_t)(kbi >> 5) * 2048 + v_src_off; \
;           __builtin_amdgcn_global_load_lds((const unsigned*)srcp, (LAS unsigned*)(ring + slot * 8192 + stage_dst), 16, 0, 0); } while (0)
; template <bool SEL, bool GEN>
; DI void attn_step(const KF& kv, const int kb, const int t, const int lane, const bool selbit,
;                   const LAS float* tabh, const half8 (&q)[2][2], f32x4 (&O)[2][4], const float (&nR)[2], float (&l)[2]) {
;     ...
;       s[hp][kt] = MFMA16(kv.k[kt][0], q[hp][0], c0);
;       s[hp][kt] = MFMA16(kv.k[kt][1], q[hp][1], s[hp][kt]);
;     }
;   }
;   if (GEN) {
;     const int d0 = t - kb - fq * 4;
; #pragma unroll
;     for (int kt = 0; kt < 2; ++kt)
; #pragma unroll
;       for (int j = 0; j < 4; ++j) {
;         const int dist = d0 - (kt * 16 + j);
;         const bool bad = SEL ? (dist < 0) : ((unsigned)dist >= 512u);
;         const int ix = bad ? 130 : (dist > 128 ? 128 : dist);
; #pragma unroll
;         for (int hp = 0; hp < 2; ++hp) s[hp][kt][j] += tabh[hp * 132 + ix];
; DI void attn_phase(const Params& p, const int layer, const int wid_s) {
;     ...
;         for (int si = 0; si < nsteps; ++si) {
;           asm volatile("s_waitcnt vmcnt(1) lgkmcnt(0)" ::: "memory");
;           __builtin_amdgcn_s_barrier();
;           asm volatile("" ::: "memory");
;           RING_ISSUE(si + 2);
;           const int kb = kb0 + si * 32;
;           if (kb > kmax_w || kb < lo_w) continue;
;           if (br == 1 && kb + 31 + 128 <= t0 && __ballot((selmask >> (kb >> 6)) & 1u) == 0ull) continue;
.Lat_yb3:
	s_waitcnt lgkmcnt(0)
	s_and_b32 s44, s12, 2
	s_or_b32 s44, s44, 1
	v_mfma_f32_16x16x32_f16 v[100:103], v[96:99], v[8:11], v[128:131]
	s_add_i32 s8, s45, 64
	s_min_i32 s8, s8, s14
	s_mul_i32 s8, s8, s42
	s_mov_b32 s9, 0
	v_mfma_f32_16x16x32_f16 v[104:107], v[88:91], v[8:11], v[128:131]
	v_lshl_add_u64 v[238:239], v[240:241], 0, s[8:9]
	s_add_i32 m0, s43, s22
	s_nop 0
	global_load_lds_dwordx4 v[238:239], off
	v_mfma_f32_16x16x32_f16 v[108:111], v[96:99], v[16:19], v[132:135]
	s_add_i32 s43, s43, 0x2000
	s_cmp_eq_u32 s43, 0x1f880
	s_cselect_b32 s43, 0x20080, s43
	s_cmp_eq_u32 s43, 0x22080
	s_cselect_b32 s43, 0x19880, s43
	v_mfma_f32_16x16x32_f16 v[112:115], v[88:91], v[16:19], v[132:135]
	s_add_i32 s45, s45, 32
	s_add_i32 s41, s41, -1
	s_add_i32 s10, s45, 0x9f
	s_cmp_gt_i32 s10, s51
	v_mfma_f32_16x16x32_f16 v[100:103], v[92:95], v[12:15], v[100:103]
	s_cselect_b32 s11, 2, 0
	s_add_i32 s10, s45, 0x1f1
	s_cmp_le_i32 s10, s51
	s_cselect_b32 s10, 2, 0
	v_mfma_f32_16x16x32_f16 v[104:107], v[84:87], v[12:15], v[104:107]
	s_and_b32 s10, s10, s4
	s_or_b32 s11, s11, s10
	s_lshr_b32 s10, s45, 6
	v_bfe_u32 v66, v244, s10, 1
	v_cmp_ne_u32_e32 vcc, 0, v66
	v_mfma_f32_16x16x32_f16 v[108:111], v[92:95], v[20:23], v[108:111]
	s_cmp_lg_u64 vcc, 0
	s_cselect_b32 s10, 1, 0
	s_lshr_b32 s9, s11, 1
	s_or_b32 s10, s10, s9
	v_mfma_f32_16x16x32_f16 v[112:115], v[84:87], v[20:23], v[112:115]
	s_cmp_le_i32 s45, s15
	s_cselect_b32 s10, s10, 0
	s_cmp_ge_i32 s45, s40
	s_cselect_b32 s10, s10, 0
	s_or_b32 s12, s11, s10
	ds_read_b128 v[80:83], v65 offset:30720
	ds_read_b128 v[76:79], v65 offset:31744
	ds_read_b128 v[72:75], v65 offset:32768
	ds_read_b128 v[68:71], v65 offset:33792
	s_bitcmp1_b32 s44, 1
	s_cbranch_scc0 .Lat_noga_yb3
	v_add_f32_e32 v100, v100, v222
	v_add_f32_e32 v101, v101, v223
	v_add_f32_e32 v102, v102, v224
	v_add_f32_e32 v103, v103, v225
	v_add_f32_e32 v104, v104, v226
	v_add_f32_e32 v105, v105, v227
	v_add_f32_e32 v106, v106, v228
	v_add_f32_e32 v107, v107, v229
	v_add_f32_e32 v108, v108, v230
	v_add_f32_e32 v109, v109, v231
	v_add_f32_e32 v110, v110, v232
	v_add_f32_e32 v111, v111, v233
	v_add_f32_e32 v112, v112, v234
	v_add_f32_e32 v113, v113, v235
	v_add_f32_e32 v114, v114, v236
	v_add_f32_e32 v115, v115, v237
